# K-loop: s_setprio 1 while a wave is in its LDS-read/DMA-issue segment (priority for the loading half instead of the MFMA half)
# baseline (speedup 1.0000x reference)
.LBB0_341:
	s_setprio 1
	s_add_u32 s36, s34, 0xfffc0080
	s_addc_u32 s37, s35, -1
	s_add_i32 s56, 0, 0x10000
	s_cmp_eq_u32 s79, 12
	s_cselect_b32 s39, s25, s37
	s_cselect_b32 s38, s31, s36
	s_cselect_b32 s37, s23, s78
	s_cselect_b32 s36, s40, s77
	s_add_i32 s80, 0, 0x14000
	v_add_u32_e32 v102, s56, v171
	v_add_u32_e32 v177, s80, v171
	ds_read_b128 v[82:85], v102
	ds_read_b128 v[86:89], v102 offset:1024
	ds_read_b128 v[94:97], v102 offset:2048
	ds_read_b128 v[102:105], v102 offset:3072
	ds_read_b128 v[134:137], v177
	ds_read_b128 v[162:165], v177 offset:1024
	ds_read_b128 v[166:169], v177 offset:2048
	ds_read_b128 v[178:181], v177 offset:3072
	v_lshl_add_u64 v[214:215], s[34:35], 0, v[158:159]
	s_add_i32 m0, s9, 0xc000
	ds_read_b128 v[182:185], v176
	ds_read_b128 v[186:189], v176 offset:1024
	ds_read_b128 v[190:193], v176 offset:2048
	ds_read_b128 v[194:197], v176 offset:3072
	ds_read_b128 v[198:201], v176 offset:4096
	ds_read_b128 v[202:205], v176 offset:5120
	ds_read_b128 v[206:209], v176 offset:6144
	ds_read_b128 v[210:213], v176 offset:7168
	global_load_lds_dwordx4 v[214:215], off
	v_lshl_add_u64 v[214:215], s[34:35], 0, v[160:161]
	s_add_i32 m0, s9, 0xe000
	s_nop 0
	global_load_lds_dwordx4 v[214:215], off
	s_waitcnt vmcnt(8)
	s_waitcnt lgkmcnt(0)
	s_setprio 0
	s_barrier
	s_waitcnt lgkmcnt(0)
	v_mfma_f32_16x16x32_bf16 v[146:149], v[82:85], v[182:185], v[146:149]
	v_mfma_f32_16x16x32_bf16 v[138:141], v[94:97], v[182:185], v[138:141]
	v_mfma_f32_16x16x32_bf16 v[126:129], v[82:85], v[190:193], v[126:129]
	v_mfma_f32_16x16x32_bf16 v[118:121], v[94:97], v[190:193], v[118:121]
	v_mfma_f32_16x16x32_bf16 v[110:113], v[82:85], v[198:201], v[110:113]
	v_mfma_f32_16x16x32_bf16 v[98:101], v[94:97], v[198:201], v[98:101]
	v_mfma_f32_16x16x32_bf16 v[78:81], v[82:85], v[206:209], v[78:81]
	v_mfma_f32_16x16x32_bf16 v[70:73], v[94:97], v[206:209], v[70:73]
	v_mfma_f32_16x16x32_bf16 v[146:149], v[86:89], v[186:189], v[146:149]
	v_mfma_f32_16x16x32_bf16 v[138:141], v[102:105], v[186:189], v[138:141]
	v_mfma_f32_16x16x32_bf16 v[126:129], v[86:89], v[194:197], v[126:129]
	v_mfma_f32_16x16x32_bf16 v[118:121], v[102:105], v[194:197], v[118:121]
	v_mfma_f32_16x16x32_bf16 v[110:113], v[86:89], v[202:205], v[110:113]
	v_mfma_f32_16x16x32_bf16 v[98:101], v[102:105], v[202:205], v[98:101]
	v_mfma_f32_16x16x32_bf16 v[78:81], v[86:89], v[210:213], v[78:81]
	v_mfma_f32_16x16x32_bf16 v[70:73], v[102:105], v[210:213], v[70:73]
	v_mfma_f32_16x16x32_bf16 v[142:145], v[134:137], v[182:185], v[142:145]
	v_mfma_f32_16x16x32_bf16 v[130:133], v[166:169], v[182:185], v[130:133]
	v_mfma_f32_16x16x32_bf16 v[122:125], v[134:137], v[190:193], v[122:125]
	v_mfma_f32_16x16x32_bf16 v[114:117], v[166:169], v[190:193], v[114:117]
	v_mfma_f32_16x16x32_bf16 v[106:109], v[134:137], v[198:201], v[106:109]
	v_mfma_f32_16x16x32_bf16 v[90:93], v[166:169], v[198:201], v[90:93]
	v_mfma_f32_16x16x32_bf16 v[74:77], v[134:137], v[206:209], v[74:77]
	v_mfma_f32_16x16x32_bf16 v[66:69], v[166:169], v[206:209], v[66:69]
	v_mfma_f32_16x16x32_bf16 v[142:145], v[162:165], v[186:189], v[142:145]
	v_mfma_f32_16x16x32_bf16 v[130:133], v[178:181], v[186:189], v[130:133]
	v_mfma_f32_16x16x32_bf16 v[122:125], v[162:165], v[194:197], v[122:125]
	v_mfma_f32_16x16x32_bf16 v[114:117], v[178:181], v[194:197], v[114:117]
	v_mfma_f32_16x16x32_bf16 v[106:109], v[162:165], v[202:205], v[106:109]
	v_mfma_f32_16x16x32_bf16 v[90:93], v[178:181], v[202:205], v[90:93]
	v_mfma_f32_16x16x32_bf16 v[74:77], v[162:165], v[210:213], v[74:77]
	v_mfma_f32_16x16x32_bf16 v[66:69], v[178:181], v[210:213], v[66:69]
	s_barrier
	s_setprio 1
	s_add_i32 s56, s56, s68
	v_lshl_add_u64 v[214:215], s[36:37], 0, v[154:155]
	s_mov_b32 m0, s56
	ds_read_b128 v[182:185], v176 offset:16384
	ds_read_b128 v[186:189], v176 offset:17408
	ds_read_b128 v[190:193], v176 offset:18432
	ds_read_b128 v[194:197], v176 offset:19456
	ds_read_b128 v[198:201], v176 offset:20480
	ds_read_b128 v[202:205], v176 offset:21504
	ds_read_b128 v[206:209], v176 offset:22528
	ds_read_b128 v[210:213], v176 offset:23552
	global_load_lds_dwordx4 v[214:215], off
	s_add_i32 m0, s56, 0x2000
	s_add_u32 s56, s36, 0x40000
	v_lshl_add_u64 v[216:217], s[36:37], 0, v[156:157]
	s_addc_u32 s57, s37, 0
	s_add_i32 s80, s80, s68
	global_load_lds_dwordx4 v[216:217], off
	v_lshl_add_u64 v[218:219], s[56:57], 0, v[154:155]
	s_mov_b32 m0, s80
	v_lshl_add_u64 v[220:221], s[38:39], 0, v[152:153]
	global_load_lds_dwordx4 v[218:219], off
	v_lshl_add_u64 v[218:219], s[56:57], 0, v[156:157]
	s_add_i32 m0, s80, 0x2000
	s_nop 0
	global_load_lds_dwordx4 v[218:219], off
	v_lshl_add_u64 v[218:219], s[38:39], 0, v[150:151]
	s_mov_b32 m0, s9
	s_nop 0
	global_load_lds_dwordx4 v[218:219], off
	s_mov_b32 m0, s69
	s_nop 0
	global_load_lds_dwordx4 v[220:221], off
	s_waitcnt vmcnt(8)
	s_waitcnt lgkmcnt(0)
	s_setprio 0
	s_barrier
	s_waitcnt lgkmcnt(0)
	v_mfma_f32_16x16x32_bf16 v[62:65], v[82:85], v[182:185], v[62:65]
	v_mfma_f32_16x16x32_bf16 v[54:57], v[94:97], v[182:185], v[54:57]
	v_mfma_f32_16x16x32_bf16 v[46:49], v[82:85], v[190:193], v[46:49]
	v_mfma_f32_16x16x32_bf16 v[38:41], v[94:97], v[190:193], v[38:41]
	v_mfma_f32_16x16x32_bf16 v[30:33], v[82:85], v[198:201], v[30:33]
	v_mfma_f32_16x16x32_bf16 v[22:25], v[94:97], v[198:201], v[22:25]
	v_mfma_f32_16x16x32_bf16 v[14:17], v[82:85], v[206:209], v[14:17]
	v_mfma_f32_16x16x32_bf16 v[6:9], v[94:97], v[206:209], v[6:9]
	v_mfma_f32_16x16x32_bf16 v[62:65], v[86:89], v[186:189], v[62:65]
	v_mfma_f32_16x16x32_bf16 v[54:57], v[102:105], v[186:189], v[54:57]
	v_mfma_f32_16x16x32_bf16 v[46:49], v[86:89], v[194:197], v[46:49]
	v_mfma_f32_16x16x32_bf16 v[38:41], v[102:105], v[194:197], v[38:41]
	v_mfma_f32_16x16x32_bf16 v[30:33], v[86:89], v[202:205], v[30:33]
	v_mfma_f32_16x16x32_bf16 v[22:25], v[102:105], v[202:205], v[22:25]
	v_mfma_f32_16x16x32_bf16 v[14:17], v[86:89], v[210:213], v[14:17]
	v_mfma_f32_16x16x32_bf16 v[6:9], v[102:105], v[210:213], v[6:9]
	v_mfma_f32_16x16x32_bf16 v[58:61], v[134:137], v[182:185], v[58:61]
	v_mfma_f32_16x16x32_bf16 v[50:53], v[166:169], v[182:185], v[50:53]
	v_mfma_f32_16x16x32_bf16 v[42:45], v[134:137], v[190:193], v[42:45]
	v_mfma_f32_16x16x32_bf16 v[34:37], v[166:169], v[190:193], v[34:37]
	v_mfma_f32_16x16x32_bf16 v[26:29], v[134:137], v[198:201], v[26:29]
	v_mfma_f32_16x16x32_bf16 v[18:21], v[166:169], v[198:201], v[18:21]
	v_mfma_f32_16x16x32_bf16 v[10:13], v[134:137], v[206:209], v[10:13]
	v_mfma_f32_16x16x32_bf16 v[2:5], v[166:169], v[206:209], v[2:5]
	v_mfma_f32_16x16x32_bf16 v[58:61], v[162:165], v[186:189], v[58:61]
	v_mfma_f32_16x16x32_bf16 v[50:53], v[178:181], v[186:189], v[50:53]
	v_mfma_f32_16x16x32_bf16 v[42:45], v[162:165], v[194:197], v[42:45]
	v_mfma_f32_16x16x32_bf16 v[34:37], v[178:181], v[194:197], v[34:37]
	v_mfma_f32_16x16x32_bf16 v[26:29], v[162:165], v[202:205], v[26:29]
	v_mfma_f32_16x16x32_bf16 v[18:21], v[178:181], v[202:205], v[18:21]
	v_mfma_f32_16x16x32_bf16 v[10:13], v[162:165], v[210:213], v[10:13]
	v_mfma_f32_16x16x32_bf16 v[2:5], v[178:181], v[210:213], v[2:5]
	s_barrier
	s_setprio 1
	s_add_i32 s56, 0, 0x18000
	s_add_i32 s57, 0, 0x1c000
	v_add_u32_e32 v102, s56, v171
	v_add_u32_e32 v177, s57, v171
	ds_read_b128 v[82:85], v102
	ds_read_b128 v[86:89], v102 offset:1024
	ds_read_b128 v[94:97], v102 offset:2048
	ds_read_b128 v[102:105], v102 offset:3072
	ds_read_b128 v[134:137], v177
	ds_read_b128 v[162:165], v177 offset:1024
	ds_read_b128 v[166:169], v177 offset:2048
	ds_read_b128 v[178:181], v177 offset:3072
	s_add_u32 s38, s38, 0x40000
	s_addc_u32 s39, s39, 0
	s_mov_b32 m0, s70
	v_lshl_add_u64 v[232:233], s[38:39], 0, v[150:151]
	ds_read_b128 v[182:185], v176 offset:32768
	ds_read_b128 v[186:189], v176 offset:33792
	ds_read_b128 v[190:193], v176 offset:34816
	ds_read_b128 v[194:197], v176 offset:35840
	ds_read_b128 v[198:201], v176 offset:36864
	ds_read_b128 v[202:205], v176 offset:37888
	ds_read_b128 v[206:209], v176 offset:38912
	ds_read_b128 v[210:213], v176 offset:39936
	global_load_lds_dwordx4 v[232:233], off
	v_lshl_add_u64 v[232:233], s[38:39], 0, v[152:153]
	s_mov_b32 m0, s71
	s_nop 0
	global_load_lds_dwordx4 v[232:233], off
	s_waitcnt vmcnt(8)
	s_waitcnt lgkmcnt(0)
	s_setprio 0
	s_barrier
	s_waitcnt lgkmcnt(0)
	v_mfma_f32_16x16x32_bf16 v[146:149], v[82:85], v[182:185], v[146:149]
	v_mfma_f32_16x16x32_bf16 v[138:141], v[94:97], v[182:185], v[138:141]
	v_mfma_f32_16x16x32_bf16 v[126:129], v[82:85], v[190:193], v[126:129]
	v_mfma_f32_16x16x32_bf16 v[118:121], v[94:97], v[190:193], v[118:121]
	v_mfma_f32_16x16x32_bf16 v[110:113], v[82:85], v[198:201], v[110:113]
	v_mfma_f32_16x16x32_bf16 v[98:101], v[94:97], v[198:201], v[98:101]
	v_mfma_f32_16x16x32_bf16 v[78:81], v[82:85], v[206:209], v[78:81]
	v_mfma_f32_16x16x32_bf16 v[70:73], v[94:97], v[206:209], v[70:73]
	v_mfma_f32_16x16x32_bf16 v[146:149], v[86:89], v[186:189], v[146:149]
	v_mfma_f32_16x16x32_bf16 v[138:141], v[102:105], v[186:189], v[138:141]
	v_mfma_f32_16x16x32_bf16 v[126:129], v[86:89], v[194:197], v[126:129]
	v_mfma_f32_16x16x32_bf16 v[118:121], v[102:105], v[194:197], v[118:121]
	v_mfma_f32_16x16x32_bf16 v[110:113], v[86:89], v[202:205], v[110:113]
	v_mfma_f32_16x16x32_bf16 v[98:101], v[102:105], v[202:205], v[98:101]
	v_mfma_f32_16x16x32_bf16 v[78:81], v[86:89], v[210:213], v[78:81]
	v_mfma_f32_16x16x32_bf16 v[70:73], v[102:105], v[210:213], v[70:73]
	v_mfma_f32_16x16x32_bf16 v[142:145], v[134:137], v[182:185], v[142:145]
	v_mfma_f32_16x16x32_bf16 v[130:133], v[166:169], v[182:185], v[130:133]
	v_mfma_f32_16x16x32_bf16 v[122:125], v[134:137], v[190:193], v[122:125]
	v_mfma_f32_16x16x32_bf16 v[114:117], v[166:169], v[190:193], v[114:117]
	v_mfma_f32_16x16x32_bf16 v[106:109], v[134:137], v[198:201], v[106:109]
	v_mfma_f32_16x16x32_bf16 v[90:93], v[166:169], v[198:201], v[90:93]
	v_mfma_f32_16x16x32_bf16 v[74:77], v[134:137], v[206:209], v[74:77]
	v_mfma_f32_16x16x32_bf16 v[66:69], v[166:169], v[206:209], v[66:69]
	v_mfma_f32_16x16x32_bf16 v[142:145], v[162:165], v[186:189], v[142:145]
	v_mfma_f32_16x16x32_bf16 v[130:133], v[178:181], v[186:189], v[130:133]
	v_mfma_f32_16x16x32_bf16 v[122:125], v[162:165], v[194:197], v[122:125]
	v_mfma_f32_16x16x32_bf16 v[114:117], v[178:181], v[194:197], v[114:117]
	v_mfma_f32_16x16x32_bf16 v[106:109], v[162:165], v[202:205], v[106:109]
	v_mfma_f32_16x16x32_bf16 v[90:93], v[178:181], v[202:205], v[90:93]
	v_mfma_f32_16x16x32_bf16 v[74:77], v[162:165], v[210:213], v[74:77]
	v_mfma_f32_16x16x32_bf16 v[66:69], v[178:181], v[210:213], v[66:69]
	s_barrier
	s_setprio 1
	s_add_i32 s38, s56, s68
	v_lshl_add_u64 v[214:215], v[214:215], 0, s[62:63]
	s_mov_b32 m0, s38
	ds_read_b128 v[182:185], v176 offset:49152
	ds_read_b128 v[186:189], v176 offset:50176
	ds_read_b128 v[190:193], v176 offset:51200
	ds_read_b128 v[194:197], v176 offset:52224
	ds_read_b128 v[198:201], v176 offset:53248
	ds_read_b128 v[202:205], v176 offset:54272
	ds_read_b128 v[206:209], v176 offset:55296
	ds_read_b128 v[210:213], v176 offset:56320
	global_load_lds_dwordx4 v[214:215], off
	s_add_i32 m0, s38, 0x2000
	s_add_u32 s36, s36, 0x40080
	v_lshl_add_u64 v[214:215], v[216:217], 0, s[62:63]
	s_addc_u32 s37, s37, 0
	s_add_i32 s38, s57, s68
	global_load_lds_dwordx4 v[214:215], off
	v_lshl_add_u64 v[214:215], s[36:37], 0, v[154:155]
	s_mov_b32 m0, s38
	s_nop 0
	global_load_lds_dwordx4 v[214:215], off
	v_lshl_add_u64 v[214:215], s[36:37], 0, v[156:157]
	s_add_i32 m0, s38, 0x2000
	s_nop 0
	global_load_lds_dwordx4 v[214:215], off
	v_lshl_add_u64 v[214:215], v[218:219], 0, s[62:63]
	s_mov_b32 m0, s73
	s_nop 0
	global_load_lds_dwordx4 v[214:215], off
	v_lshl_add_u64 v[214:215], v[220:221], 0, s[62:63]
	s_mov_b32 m0, s74
	s_nop 0
	global_load_lds_dwordx4 v[214:215], off
	s_waitcnt vmcnt(8)
	s_waitcnt lgkmcnt(0)
	s_setprio 0
	s_barrier
	s_waitcnt lgkmcnt(0)
	v_mfma_f32_16x16x32_bf16 v[62:65], v[82:85], v[182:185], v[62:65]
	v_mfma_f32_16x16x32_bf16 v[54:57], v[94:97], v[182:185], v[54:57]
	v_mfma_f32_16x16x32_bf16 v[46:49], v[82:85], v[190:193], v[46:49]
	v_mfma_f32_16x16x32_bf16 v[38:41], v[94:97], v[190:193], v[38:41]
	v_mfma_f32_16x16x32_bf16 v[30:33], v[82:85], v[198:201], v[30:33]
	v_mfma_f32_16x16x32_bf16 v[22:25], v[94:97], v[198:201], v[22:25]
	v_mfma_f32_16x16x32_bf16 v[14:17], v[82:85], v[206:209], v[14:17]
	v_mfma_f32_16x16x32_bf16 v[6:9], v[94:97], v[206:209], v[6:9]
	v_mfma_f32_16x16x32_bf16 v[62:65], v[86:89], v[186:189], v[62:65]
	v_mfma_f32_16x16x32_bf16 v[54:57], v[102:105], v[186:189], v[54:57]
	v_mfma_f32_16x16x32_bf16 v[46:49], v[86:89], v[194:197], v[46:49]
	v_mfma_f32_16x16x32_bf16 v[38:41], v[102:105], v[194:197], v[38:41]
	v_mfma_f32_16x16x32_bf16 v[30:33], v[86:89], v[202:205], v[30:33]
	v_mfma_f32_16x16x32_bf16 v[22:25], v[102:105], v[202:205], v[22:25]
	v_mfma_f32_16x16x32_bf16 v[14:17], v[86:89], v[210:213], v[14:17]
	v_mfma_f32_16x16x32_bf16 v[6:9], v[102:105], v[210:213], v[6:9]
	v_mfma_f32_16x16x32_bf16 v[58:61], v[134:137], v[182:185], v[58:61]
	v_mfma_f32_16x16x32_bf16 v[50:53], v[166:169], v[182:185], v[50:53]
	v_mfma_f32_16x16x32_bf16 v[42:45], v[134:137], v[190:193], v[42:45]
	v_mfma_f32_16x16x32_bf16 v[34:37], v[166:169], v[190:193], v[34:37]
	v_mfma_f32_16x16x32_bf16 v[26:29], v[134:137], v[198:201], v[26:29]
	v_mfma_f32_16x16x32_bf16 v[18:21], v[166:169], v[198:201], v[18:21]
	v_mfma_f32_16x16x32_bf16 v[10:13], v[134:137], v[206:209], v[10:13]
	v_mfma_f32_16x16x32_bf16 v[2:5], v[166:169], v[206:209], v[2:5]
	v_mfma_f32_16x16x32_bf16 v[58:61], v[162:165], v[186:189], v[58:61]
	v_mfma_f32_16x16x32_bf16 v[50:53], v[178:181], v[186:189], v[50:53]
	v_mfma_f32_16x16x32_bf16 v[42:45], v[162:165], v[194:197], v[42:45]
	v_mfma_f32_16x16x32_bf16 v[34:37], v[178:181], v[194:197], v[34:37]
	v_mfma_f32_16x16x32_bf16 v[26:29], v[162:165], v[202:205], v[26:29]
	v_mfma_f32_16x16x32_bf16 v[18:21], v[178:181], v[202:205], v[18:21]
	v_mfma_f32_16x16x32_bf16 v[10:13], v[162:165], v[210:213], v[10:13]
	v_mfma_f32_16x16x32_bf16 v[2:5], v[178:181], v[210:213], v[2:5]
	s_barrier
	s_add_i32 s79, s79, 2
	s_add_u32 s34, s34, 0x100
	s_addc_u32 s35, s35, 0
	s_add_u32 s77, s77, 0x100
	s_addc_u32 s78, s78, 0
	s_cmp_gt_u32 s79, 13
	s_cbranch_scc0 .LBB0_341
	s_and_b64 vcc, exec, s[18:19]
	s_cbranch_vccz .LBB0_344
	s_barrier

.LBB0_445:
	s_setprio 1
	s_add_u32 s22, s20, 0xfffc0080
	s_addc_u32 s23, s21, -1
	s_add_i32 s56, 0, 0x10000
	s_cmp_eq_u32 s70, 12
	s_cselect_b32 s25, s13, s23
	s_cselect_b32 s24, s66, s22
	v_add_u32_e32 v152, s56, v145
	s_cselect_b32 s23, s11, s69
	s_cselect_b32 s22, s67, s68
	s_add_i32 s71, 0, 0x14000
	ds_read_b128 v[140:143], v152
	ds_read_b128 v[148:151], v152 offset:1024
	ds_read_b128 v[156:159], v152 offset:2048
	ds_read_b128 v[160:163], v152 offset:3072
	v_add_u32_e32 v152, s71, v145
	ds_read_b128 v[164:167], v152
	ds_read_b128 v[168:171], v152 offset:1024
	ds_read_b128 v[172:175], v152 offset:2048
	ds_read_b128 v[176:179], v152 offset:3072
	v_lshl_add_u64 v[152:153], s[20:21], 0, v[136:137]
	s_add_i32 m0, s19, 0xc000
	ds_read_b128 v[180:183], v147
	ds_read_b128 v[184:187], v147 offset:1024
	ds_read_b128 v[188:191], v147 offset:2048
	ds_read_b128 v[192:195], v147 offset:3072
	ds_read_b128 v[196:199], v147 offset:4096
	ds_read_b128 v[200:203], v147 offset:5120
	ds_read_b128 v[204:207], v147 offset:6144
	ds_read_b128 v[208:211], v147 offset:7168
	global_load_lds_dwordx4 v[152:153], off
	v_lshl_add_u64 v[152:153], s[20:21], 0, v[138:139]
	s_add_i32 m0, s19, 0xe000
	s_nop 0
	global_load_lds_dwordx4 v[152:153], off
	s_waitcnt vmcnt(8)
	s_waitcnt lgkmcnt(0)
	s_setprio 0
	s_barrier
	s_waitcnt lgkmcnt(0)
	v_mfma_f32_16x16x32_bf16 v[126:129], v[140:143], v[180:183], v[126:129]
	v_mfma_f32_16x16x32_bf16 v[122:125], v[156:159], v[180:183], v[122:125]
	v_mfma_f32_16x16x32_bf16 v[110:113], v[140:143], v[188:191], v[110:113]
	v_mfma_f32_16x16x32_bf16 v[106:109], v[156:159], v[188:191], v[106:109]
	v_mfma_f32_16x16x32_bf16 v[94:97], v[140:143], v[196:199], v[94:97]
	v_mfma_f32_16x16x32_bf16 v[90:93], v[156:159], v[196:199], v[90:93]
	v_mfma_f32_16x16x32_bf16 v[78:81], v[140:143], v[204:207], v[78:81]
	v_mfma_f32_16x16x32_bf16 v[74:77], v[156:159], v[204:207], v[74:77]
	v_mfma_f32_16x16x32_bf16 v[126:129], v[148:151], v[184:187], v[126:129]
	v_mfma_f32_16x16x32_bf16 v[122:125], v[160:163], v[184:187], v[122:125]
	v_mfma_f32_16x16x32_bf16 v[110:113], v[148:151], v[192:195], v[110:113]
	v_mfma_f32_16x16x32_bf16 v[106:109], v[160:163], v[192:195], v[106:109]
	v_mfma_f32_16x16x32_bf16 v[94:97], v[148:151], v[200:203], v[94:97]
	v_mfma_f32_16x16x32_bf16 v[90:93], v[160:163], v[200:203], v[90:93]
	v_mfma_f32_16x16x32_bf16 v[78:81], v[148:151], v[208:211], v[78:81]
	v_mfma_f32_16x16x32_bf16 v[74:77], v[160:163], v[208:211], v[74:77]
	v_mfma_f32_16x16x32_bf16 v[118:121], v[164:167], v[180:183], v[118:121]
	v_mfma_f32_16x16x32_bf16 v[114:117], v[172:175], v[180:183], v[114:117]
	v_mfma_f32_16x16x32_bf16 v[102:105], v[164:167], v[188:191], v[102:105]
	v_mfma_f32_16x16x32_bf16 v[98:101], v[172:175], v[188:191], v[98:101]
	v_mfma_f32_16x16x32_bf16 v[86:89], v[164:167], v[196:199], v[86:89]
	v_mfma_f32_16x16x32_bf16 v[82:85], v[172:175], v[196:199], v[82:85]
	v_mfma_f32_16x16x32_bf16 v[70:73], v[164:167], v[204:207], v[70:73]
	v_mfma_f32_16x16x32_bf16 v[66:69], v[172:175], v[204:207], v[66:69]
	v_mfma_f32_16x16x32_bf16 v[118:121], v[168:171], v[184:187], v[118:121]
	v_mfma_f32_16x16x32_bf16 v[114:117], v[176:179], v[184:187], v[114:117]
	v_mfma_f32_16x16x32_bf16 v[102:105], v[168:171], v[192:195], v[102:105]
	v_mfma_f32_16x16x32_bf16 v[98:101], v[176:179], v[192:195], v[98:101]
	v_mfma_f32_16x16x32_bf16 v[86:89], v[168:171], v[200:203], v[86:89]
	v_mfma_f32_16x16x32_bf16 v[82:85], v[176:179], v[200:203], v[82:85]
	v_mfma_f32_16x16x32_bf16 v[70:73], v[168:171], v[208:211], v[70:73]
	v_mfma_f32_16x16x32_bf16 v[66:69], v[176:179], v[208:211], v[66:69]
	s_barrier
	s_setprio 1
	s_add_i32 s56, s56, s35
	v_lshl_add_u64 v[152:153], s[22:23], 0, v[154:155]
	s_mov_b32 m0, s56
	ds_read_b128 v[180:183], v147 offset:16384
	ds_read_b128 v[184:187], v147 offset:17408
	ds_read_b128 v[188:191], v147 offset:18432
	ds_read_b128 v[192:195], v147 offset:19456
	ds_read_b128 v[196:199], v147 offset:20480
	ds_read_b128 v[200:203], v147 offset:21504
	ds_read_b128 v[204:207], v147 offset:22528
	ds_read_b128 v[208:211], v147 offset:23552
	global_load_lds_dwordx4 v[152:153], off
	s_add_i32 m0, s56, 0x2000
	s_add_u32 s56, s22, 0x40000
	v_lshl_add_u64 v[212:213], s[22:23], 0, v[134:135]
	s_addc_u32 s57, s23, 0
	s_add_i32 s71, s71, s35
	global_load_lds_dwordx4 v[212:213], off
	v_lshl_add_u64 v[214:215], s[56:57], 0, v[154:155]
	s_mov_b32 m0, s71
	v_lshl_add_u64 v[216:217], s[24:25], 0, v[132:133]
	global_load_lds_dwordx4 v[214:215], off
	v_lshl_add_u64 v[214:215], s[56:57], 0, v[134:135]
	s_add_i32 m0, s71, 0x2000
	s_nop 0
	global_load_lds_dwordx4 v[214:215], off
	v_lshl_add_u64 v[214:215], s[24:25], 0, v[130:131]
	s_mov_b32 m0, s19
	s_nop 0
	global_load_lds_dwordx4 v[214:215], off
	s_mov_b32 m0, s36
	s_nop 0
	global_load_lds_dwordx4 v[216:217], off
	s_waitcnt vmcnt(8)
	s_waitcnt lgkmcnt(0)
	s_setprio 0
	s_barrier
	s_waitcnt lgkmcnt(0)
	v_mfma_f32_16x16x32_bf16 v[62:65], v[140:143], v[180:183], v[62:65]
	v_mfma_f32_16x16x32_bf16 v[58:61], v[156:159], v[180:183], v[58:61]
	v_mfma_f32_16x16x32_bf16 v[46:49], v[140:143], v[188:191], v[46:49]
	v_mfma_f32_16x16x32_bf16 v[42:45], v[156:159], v[188:191], v[42:45]
	v_mfma_f32_16x16x32_bf16 v[30:33], v[140:143], v[196:199], v[30:33]
	v_mfma_f32_16x16x32_bf16 v[26:29], v[156:159], v[196:199], v[26:29]
	v_mfma_f32_16x16x32_bf16 v[14:17], v[140:143], v[204:207], v[14:17]
	v_mfma_f32_16x16x32_bf16 v[10:13], v[156:159], v[204:207], v[10:13]
	v_mfma_f32_16x16x32_bf16 v[62:65], v[148:151], v[184:187], v[62:65]
	v_mfma_f32_16x16x32_bf16 v[58:61], v[160:163], v[184:187], v[58:61]
	v_mfma_f32_16x16x32_bf16 v[46:49], v[148:151], v[192:195], v[46:49]
	v_mfma_f32_16x16x32_bf16 v[42:45], v[160:163], v[192:195], v[42:45]
	v_mfma_f32_16x16x32_bf16 v[30:33], v[148:151], v[200:203], v[30:33]
	v_mfma_f32_16x16x32_bf16 v[26:29], v[160:163], v[200:203], v[26:29]
	v_mfma_f32_16x16x32_bf16 v[14:17], v[148:151], v[208:211], v[14:17]
	v_mfma_f32_16x16x32_bf16 v[10:13], v[160:163], v[208:211], v[10:13]
	v_mfma_f32_16x16x32_bf16 v[54:57], v[164:167], v[180:183], v[54:57]
	v_mfma_f32_16x16x32_bf16 v[50:53], v[172:175], v[180:183], v[50:53]
	v_mfma_f32_16x16x32_bf16 v[38:41], v[164:167], v[188:191], v[38:41]
	v_mfma_f32_16x16x32_bf16 v[34:37], v[172:175], v[188:191], v[34:37]
	v_mfma_f32_16x16x32_bf16 v[22:25], v[164:167], v[196:199], v[22:25]
	v_mfma_f32_16x16x32_bf16 v[18:21], v[172:175], v[196:199], v[18:21]
	v_mfma_f32_16x16x32_bf16 v[6:9], v[164:167], v[204:207], v[6:9]
	v_mfma_f32_16x16x32_bf16 v[2:5], v[172:175], v[204:207], v[2:5]
	v_mfma_f32_16x16x32_bf16 v[54:57], v[168:171], v[184:187], v[54:57]
	v_mfma_f32_16x16x32_bf16 v[50:53], v[176:179], v[184:187], v[50:53]
	v_mfma_f32_16x16x32_bf16 v[38:41], v[168:171], v[192:195], v[38:41]
	v_mfma_f32_16x16x32_bf16 v[34:37], v[176:179], v[192:195], v[34:37]
	v_mfma_f32_16x16x32_bf16 v[22:25], v[168:171], v[200:203], v[22:25]
	v_mfma_f32_16x16x32_bf16 v[18:21], v[176:179], v[200:203], v[18:21]
	v_mfma_f32_16x16x32_bf16 v[6:9], v[168:171], v[208:211], v[6:9]
	v_mfma_f32_16x16x32_bf16 v[2:5], v[176:179], v[208:211], v[2:5]
	s_barrier
	s_setprio 1
	s_add_i32 s56, 0, 0x18000
	s_add_i32 s57, 0, 0x1c000
	v_add_u32_e32 v160, s56, v145
	v_add_u32_e32 v176, s57, v145
	ds_read_b128 v[140:143], v160
	ds_read_b128 v[148:151], v160 offset:1024
	ds_read_b128 v[156:159], v160 offset:2048
	ds_read_b128 v[160:163], v160 offset:3072
	ds_read_b128 v[164:167], v176
	ds_read_b128 v[168:171], v176 offset:1024
	ds_read_b128 v[172:175], v176 offset:2048
	ds_read_b128 v[176:179], v176 offset:3072
	s_add_u32 s24, s24, 0x40000
	s_addc_u32 s25, s25, 0
	s_mov_b32 m0, s37
	v_lshl_add_u64 v[218:219], s[24:25], 0, v[130:131]
	ds_read_b128 v[180:183], v147 offset:32768
	ds_read_b128 v[184:187], v147 offset:33792
	ds_read_b128 v[188:191], v147 offset:34816
	ds_read_b128 v[192:195], v147 offset:35840
	ds_read_b128 v[196:199], v147 offset:36864
	ds_read_b128 v[200:203], v147 offset:37888
	ds_read_b128 v[204:207], v147 offset:38912
	ds_read_b128 v[208:211], v147 offset:39936
	global_load_lds_dwordx4 v[218:219], off
	v_lshl_add_u64 v[218:219], s[24:25], 0, v[132:133]
	s_mov_b32 m0, s38
	s_nop 0
	global_load_lds_dwordx4 v[218:219], off
	s_waitcnt vmcnt(8)
	s_waitcnt lgkmcnt(0)
	s_setprio 0
	s_barrier
	s_waitcnt lgkmcnt(0)
	v_mfma_f32_16x16x32_bf16 v[126:129], v[140:143], v[180:183], v[126:129]
	v_mfma_f32_16x16x32_bf16 v[122:125], v[156:159], v[180:183], v[122:125]
	v_mfma_f32_16x16x32_bf16 v[110:113], v[140:143], v[188:191], v[110:113]
	v_mfma_f32_16x16x32_bf16 v[106:109], v[156:159], v[188:191], v[106:109]
	v_mfma_f32_16x16x32_bf16 v[94:97], v[140:143], v[196:199], v[94:97]
	v_mfma_f32_16x16x32_bf16 v[90:93], v[156:159], v[196:199], v[90:93]
	v_mfma_f32_16x16x32_bf16 v[78:81], v[140:143], v[204:207], v[78:81]
	v_mfma_f32_16x16x32_bf16 v[74:77], v[156:159], v[204:207], v[74:77]
	v_mfma_f32_16x16x32_bf16 v[126:129], v[148:151], v[184:187], v[126:129]
	v_mfma_f32_16x16x32_bf16 v[122:125], v[160:163], v[184:187], v[122:125]
	v_mfma_f32_16x16x32_bf16 v[110:113], v[148:151], v[192:195], v[110:113]
	v_mfma_f32_16x16x32_bf16 v[106:109], v[160:163], v[192:195], v[106:109]
	v_mfma_f32_16x16x32_bf16 v[94:97], v[148:151], v[200:203], v[94:97]
	v_mfma_f32_16x16x32_bf16 v[90:93], v[160:163], v[200:203], v[90:93]
	v_mfma_f32_16x16x32_bf16 v[78:81], v[148:151], v[208:211], v[78:81]
	v_mfma_f32_16x16x32_bf16 v[74:77], v[160:163], v[208:211], v[74:77]
	v_mfma_f32_16x16x32_bf16 v[118:121], v[164:167], v[180:183], v[118:121]
	v_mfma_f32_16x16x32_bf16 v[114:117], v[172:175], v[180:183], v[114:117]
	v_mfma_f32_16x16x32_bf16 v[102:105], v[164:167], v[188:191], v[102:105]
	v_mfma_f32_16x16x32_bf16 v[98:101], v[172:175], v[188:191], v[98:101]
	v_mfma_f32_16x16x32_bf16 v[86:89], v[164:167], v[196:199], v[86:89]
	v_mfma_f32_16x16x32_bf16 v[82:85], v[172:175], v[196:199], v[82:85]
	v_mfma_f32_16x16x32_bf16 v[70:73], v[164:167], v[204:207], v[70:73]
	v_mfma_f32_16x16x32_bf16 v[66:69], v[172:175], v[204:207], v[66:69]
	v_mfma_f32_16x16x32_bf16 v[118:121], v[168:171], v[184:187], v[118:121]
	v_mfma_f32_16x16x32_bf16 v[114:117], v[176:179], v[184:187], v[114:117]
	v_mfma_f32_16x16x32_bf16 v[102:105], v[168:171], v[192:195], v[102:105]
	v_mfma_f32_16x16x32_bf16 v[98:101], v[176:179], v[192:195], v[98:101]
	v_mfma_f32_16x16x32_bf16 v[86:89], v[168:171], v[200:203], v[86:89]
	v_mfma_f32_16x16x32_bf16 v[82:85], v[176:179], v[200:203], v[82:85]
	v_mfma_f32_16x16x32_bf16 v[70:73], v[168:171], v[208:211], v[70:73]
	v_mfma_f32_16x16x32_bf16 v[66:69], v[176:179], v[208:211], v[66:69]
	s_barrier
	s_setprio 1
	s_add_i32 s24, s56, s35
	v_lshl_add_u64 v[152:153], v[152:153], 0, s[62:63]
	s_mov_b32 m0, s24
	ds_read_b128 v[180:183], v147 offset:49152
	ds_read_b128 v[184:187], v147 offset:50176
	ds_read_b128 v[188:191], v147 offset:51200
	ds_read_b128 v[192:195], v147 offset:52224
	ds_read_b128 v[196:199], v147 offset:53248
	ds_read_b128 v[200:203], v147 offset:54272
	ds_read_b128 v[204:207], v147 offset:55296
	ds_read_b128 v[208:211], v147 offset:56320
	global_load_lds_dwordx4 v[152:153], off
	s_add_i32 m0, s24, 0x2000
	s_add_u32 s22, s22, 0x40080
	v_lshl_add_u64 v[152:153], v[212:213], 0, s[62:63]
	s_addc_u32 s23, s23, 0
	s_add_i32 s24, s57, s35
	global_load_lds_dwordx4 v[152:153], off
	v_lshl_add_u64 v[152:153], s[22:23], 0, v[154:155]
	s_mov_b32 m0, s24
	s_nop 0
	global_load_lds_dwordx4 v[152:153], off
	v_lshl_add_u64 v[152:153], s[22:23], 0, v[134:135]
	s_add_i32 m0, s24, 0x2000
	s_nop 0
	global_load_lds_dwordx4 v[152:153], off
	v_lshl_add_u64 v[152:153], v[214:215], 0, s[62:63]
	s_mov_b32 m0, s39
	s_nop 0
	global_load_lds_dwordx4 v[152:153], off
	v_lshl_add_u64 v[152:153], v[216:217], 0, s[62:63]
	s_mov_b32 m0, s40
	s_nop 0
	global_load_lds_dwordx4 v[152:153], off
	s_waitcnt vmcnt(8)
	s_waitcnt lgkmcnt(0)
	s_setprio 0
	s_barrier
	s_waitcnt lgkmcnt(0)
	v_mfma_f32_16x16x32_bf16 v[62:65], v[140:143], v[180:183], v[62:65]
	v_mfma_f32_16x16x32_bf16 v[58:61], v[156:159], v[180:183], v[58:61]
	v_mfma_f32_16x16x32_bf16 v[46:49], v[140:143], v[188:191], v[46:49]
	v_mfma_f32_16x16x32_bf16 v[42:45], v[156:159], v[188:191], v[42:45]
	v_mfma_f32_16x16x32_bf16 v[30:33], v[140:143], v[196:199], v[30:33]
	v_mfma_f32_16x16x32_bf16 v[26:29], v[156:159], v[196:199], v[26:29]
	v_mfma_f32_16x16x32_bf16 v[14:17], v[140:143], v[204:207], v[14:17]
	v_mfma_f32_16x16x32_bf16 v[10:13], v[156:159], v[204:207], v[10:13]
	v_mfma_f32_16x16x32_bf16 v[62:65], v[148:151], v[184:187], v[62:65]
	v_mfma_f32_16x16x32_bf16 v[58:61], v[160:163], v[184:187], v[58:61]
	v_mfma_f32_16x16x32_bf16 v[46:49], v[148:151], v[192:195], v[46:49]
	v_mfma_f32_16x16x32_bf16 v[42:45], v[160:163], v[192:195], v[42:45]
	v_mfma_f32_16x16x32_bf16 v[30:33], v[148:151], v[200:203], v[30:33]
	v_mfma_f32_16x16x32_bf16 v[26:29], v[160:163], v[200:203], v[26:29]
	v_mfma_f32_16x16x32_bf16 v[14:17], v[148:151], v[208:211], v[14:17]
	v_mfma_f32_16x16x32_bf16 v[10:13], v[160:163], v[208:211], v[10:13]
	v_mfma_f32_16x16x32_bf16 v[54:57], v[164:167], v[180:183], v[54:57]
	v_mfma_f32_16x16x32_bf16 v[50:53], v[172:175], v[180:183], v[50:53]
	v_mfma_f32_16x16x32_bf16 v[38:41], v[164:167], v[188:191], v[38:41]
	v_mfma_f32_16x16x32_bf16 v[34:37], v[172:175], v[188:191], v[34:37]
	v_mfma_f32_16x16x32_bf16 v[22:25], v[164:167], v[196:199], v[22:25]
	v_mfma_f32_16x16x32_bf16 v[18:21], v[172:175], v[196:199], v[18:21]
	v_mfma_f32_16x16x32_bf16 v[6:9], v[164:167], v[204:207], v[6:9]
	v_mfma_f32_16x16x32_bf16 v[2:5], v[172:175], v[204:207], v[2:5]
	v_mfma_f32_16x16x32_bf16 v[54:57], v[168:171], v[184:187], v[54:57]
	v_mfma_f32_16x16x32_bf16 v[50:53], v[176:179], v[184:187], v[50:53]
	v_mfma_f32_16x16x32_bf16 v[38:41], v[168:171], v[192:195], v[38:41]
	v_mfma_f32_16x16x32_bf16 v[34:37], v[176:179], v[192:195], v[34:37]
	v_mfma_f32_16x16x32_bf16 v[22:25], v[168:171], v[200:203], v[22:25]
	v_mfma_f32_16x16x32_bf16 v[18:21], v[176:179], v[200:203], v[18:21]
	v_mfma_f32_16x16x32_bf16 v[6:9], v[168:171], v[208:211], v[6:9]
	v_mfma_f32_16x16x32_bf16 v[2:5], v[176:179], v[208:211], v[2:5]
	s_barrier
	s_add_i32 s70, s70, 2
	s_add_u32 s20, s20, 0x100
	s_addc_u32 s21, s21, 0
	s_add_u32 s68, s68, 0x100
	s_addc_u32 s69, s69, 0
	s_cmp_gt_u32 s70, 13
	s_cbranch_scc0 .LBB0_445
	s_and_b64 vcc, exec, s[8:9]
	s_cbranch_vccz .LBB0_448
	s_barrier

.LBB0_534:
	s_setprio 1
	s_add_u32 s24, s22, 0xfff00080
	s_addc_u32 s25, s23, -1
	s_add_i32 s56, 0, 0x10000
	s_cmp_eq_u32 s69, 60
	s_cselect_b32 s27, s13, s25
	s_cselect_b32 s26, s19, s24
	v_add_u32_e32 v152, s56, v159
	s_cselect_b32 s25, s11, s68
	s_cselect_b32 s24, s21, s40
	s_add_i32 s70, 0, 0x14000
	ds_read_b128 v[130:133], v152
	ds_read_b128 v[134:137], v152 offset:1024
	ds_read_b128 v[148:151], v152 offset:2048
	ds_read_b128 v[162:165], v152 offset:3072
	v_add_u32_e32 v152, s70, v159
	ds_read_b128 v[166:169], v152
	ds_read_b128 v[170:173], v152 offset:1024
	ds_read_b128 v[174:177], v152 offset:2048
	ds_read_b128 v[178:181], v152 offset:3072
	v_lshl_add_u64 v[152:153], s[22:23], 0, v[144:145]
	s_add_i32 m0, s38, 0xc000
	ds_read_b128 v[182:185], v161
	ds_read_b128 v[186:189], v161 offset:1024
	ds_read_b128 v[190:193], v161 offset:2048
	ds_read_b128 v[194:197], v161 offset:3072
	ds_read_b128 v[198:201], v161 offset:4096
	ds_read_b128 v[202:205], v161 offset:5120
	ds_read_b128 v[206:209], v161 offset:6144
	ds_read_b128 v[210:213], v161 offset:7168
	global_load_lds_dwordx4 v[152:153], off
	v_lshl_add_u64 v[152:153], s[22:23], 0, v[146:147]
	s_add_i32 m0, s38, 0xe000
	s_nop 0
	global_load_lds_dwordx4 v[152:153], off
	s_waitcnt vmcnt(8)
	s_waitcnt lgkmcnt(0)
	s_setprio 0
	s_barrier
	s_waitcnt lgkmcnt(0)
	v_mfma_f32_16x16x32_bf16 v[126:129], v[130:133], v[182:185], v[126:129]
	v_mfma_f32_16x16x32_bf16 v[122:125], v[148:151], v[182:185], v[122:125]
	v_mfma_f32_16x16x32_bf16 v[110:113], v[130:133], v[190:193], v[110:113]
	v_mfma_f32_16x16x32_bf16 v[106:109], v[148:151], v[190:193], v[106:109]
	v_mfma_f32_16x16x32_bf16 v[94:97], v[130:133], v[198:201], v[94:97]
	v_mfma_f32_16x16x32_bf16 v[90:93], v[148:151], v[198:201], v[90:93]
	v_mfma_f32_16x16x32_bf16 v[78:81], v[130:133], v[206:209], v[78:81]
	v_mfma_f32_16x16x32_bf16 v[74:77], v[148:151], v[206:209], v[74:77]
	v_mfma_f32_16x16x32_bf16 v[126:129], v[134:137], v[186:189], v[126:129]
	v_mfma_f32_16x16x32_bf16 v[122:125], v[162:165], v[186:189], v[122:125]
	v_mfma_f32_16x16x32_bf16 v[110:113], v[134:137], v[194:197], v[110:113]
	v_mfma_f32_16x16x32_bf16 v[106:109], v[162:165], v[194:197], v[106:109]
	v_mfma_f32_16x16x32_bf16 v[94:97], v[134:137], v[202:205], v[94:97]
	v_mfma_f32_16x16x32_bf16 v[90:93], v[162:165], v[202:205], v[90:93]
	v_mfma_f32_16x16x32_bf16 v[78:81], v[134:137], v[210:213], v[78:81]
	v_mfma_f32_16x16x32_bf16 v[74:77], v[162:165], v[210:213], v[74:77]
	v_mfma_f32_16x16x32_bf16 v[118:121], v[166:169], v[182:185], v[118:121]
	v_mfma_f32_16x16x32_bf16 v[114:117], v[174:177], v[182:185], v[114:117]
	v_mfma_f32_16x16x32_bf16 v[102:105], v[166:169], v[190:193], v[102:105]
	v_mfma_f32_16x16x32_bf16 v[98:101], v[174:177], v[190:193], v[98:101]
	v_mfma_f32_16x16x32_bf16 v[86:89], v[166:169], v[198:201], v[86:89]
	v_mfma_f32_16x16x32_bf16 v[82:85], v[174:177], v[198:201], v[82:85]
	v_mfma_f32_16x16x32_bf16 v[70:73], v[166:169], v[206:209], v[70:73]
	v_mfma_f32_16x16x32_bf16 v[66:69], v[174:177], v[206:209], v[66:69]
	v_mfma_f32_16x16x32_bf16 v[118:121], v[170:173], v[186:189], v[118:121]
	v_mfma_f32_16x16x32_bf16 v[114:117], v[178:181], v[186:189], v[114:117]
	v_mfma_f32_16x16x32_bf16 v[102:105], v[170:173], v[194:197], v[102:105]
	v_mfma_f32_16x16x32_bf16 v[98:101], v[178:181], v[194:197], v[98:101]
	v_mfma_f32_16x16x32_bf16 v[86:89], v[170:173], v[202:205], v[86:89]
	v_mfma_f32_16x16x32_bf16 v[82:85], v[178:181], v[202:205], v[82:85]
	v_mfma_f32_16x16x32_bf16 v[70:73], v[170:173], v[210:213], v[70:73]
	v_mfma_f32_16x16x32_bf16 v[66:69], v[178:181], v[210:213], v[66:69]
	s_barrier
	s_setprio 1
	s_add_i32 s56, s56, s37
	v_lshl_add_u64 v[152:153], s[24:25], 0, v[154:155]
	s_mov_b32 m0, s56
	ds_read_b128 v[182:185], v161 offset:16384
	ds_read_b128 v[186:189], v161 offset:17408
	ds_read_b128 v[190:193], v161 offset:18432
	ds_read_b128 v[194:197], v161 offset:19456
	ds_read_b128 v[198:201], v161 offset:20480
	ds_read_b128 v[202:205], v161 offset:21504
	ds_read_b128 v[206:209], v161 offset:22528
	ds_read_b128 v[210:213], v161 offset:23552
	global_load_lds_dwordx4 v[152:153], off
	s_add_i32 m0, s56, 0x2000
	s_add_u32 s56, s24, 0x100000
	v_lshl_add_u64 v[156:157], s[24:25], 0, v[142:143]
	s_addc_u32 s57, s25, 0
	s_add_i32 s70, s70, s37
	global_load_lds_dwordx4 v[156:157], off
	v_lshl_add_u64 v[214:215], s[56:57], 0, v[154:155]
	s_mov_b32 m0, s70
	v_lshl_add_u64 v[216:217], s[26:27], 0, v[140:141]
	global_load_lds_dwordx4 v[214:215], off
	v_lshl_add_u64 v[214:215], s[56:57], 0, v[142:143]
	s_add_i32 m0, s70, 0x2000
	s_nop 0
	global_load_lds_dwordx4 v[214:215], off
	v_lshl_add_u64 v[214:215], s[26:27], 0, v[138:139]
	s_mov_b32 m0, s38
	s_nop 0
	global_load_lds_dwordx4 v[214:215], off
	s_mov_b32 m0, s39
	s_nop 0
	global_load_lds_dwordx4 v[216:217], off
	s_waitcnt vmcnt(8)
	s_waitcnt lgkmcnt(0)
	s_setprio 0
	s_barrier
	s_waitcnt lgkmcnt(0)
	v_mfma_f32_16x16x32_bf16 v[62:65], v[130:133], v[182:185], v[62:65]
	v_mfma_f32_16x16x32_bf16 v[58:61], v[148:151], v[182:185], v[58:61]
	v_mfma_f32_16x16x32_bf16 v[46:49], v[130:133], v[190:193], v[46:49]
	v_mfma_f32_16x16x32_bf16 v[42:45], v[148:151], v[190:193], v[42:45]
	v_mfma_f32_16x16x32_bf16 v[30:33], v[130:133], v[198:201], v[30:33]
	v_mfma_f32_16x16x32_bf16 v[26:29], v[148:151], v[198:201], v[26:29]
	v_mfma_f32_16x16x32_bf16 v[14:17], v[130:133], v[206:209], v[14:17]
	v_mfma_f32_16x16x32_bf16 v[10:13], v[148:151], v[206:209], v[10:13]
	v_mfma_f32_16x16x32_bf16 v[62:65], v[134:137], v[186:189], v[62:65]
	v_mfma_f32_16x16x32_bf16 v[58:61], v[162:165], v[186:189], v[58:61]
	v_mfma_f32_16x16x32_bf16 v[46:49], v[134:137], v[194:197], v[46:49]
	v_mfma_f32_16x16x32_bf16 v[42:45], v[162:165], v[194:197], v[42:45]
	v_mfma_f32_16x16x32_bf16 v[30:33], v[134:137], v[202:205], v[30:33]
	v_mfma_f32_16x16x32_bf16 v[26:29], v[162:165], v[202:205], v[26:29]
	v_mfma_f32_16x16x32_bf16 v[14:17], v[134:137], v[210:213], v[14:17]
	v_mfma_f32_16x16x32_bf16 v[10:13], v[162:165], v[210:213], v[10:13]
	v_mfma_f32_16x16x32_bf16 v[54:57], v[166:169], v[182:185], v[54:57]
	v_mfma_f32_16x16x32_bf16 v[50:53], v[174:177], v[182:185], v[50:53]
	v_mfma_f32_16x16x32_bf16 v[38:41], v[166:169], v[190:193], v[38:41]
	v_mfma_f32_16x16x32_bf16 v[34:37], v[174:177], v[190:193], v[34:37]
	v_mfma_f32_16x16x32_bf16 v[22:25], v[166:169], v[198:201], v[22:25]
	v_mfma_f32_16x16x32_bf16 v[18:21], v[174:177], v[198:201], v[18:21]
	v_mfma_f32_16x16x32_bf16 v[6:9], v[166:169], v[206:209], v[6:9]
	v_mfma_f32_16x16x32_bf16 v[2:5], v[174:177], v[206:209], v[2:5]
	v_mfma_f32_16x16x32_bf16 v[54:57], v[170:173], v[186:189], v[54:57]
	v_mfma_f32_16x16x32_bf16 v[50:53], v[178:181], v[186:189], v[50:53]
	v_mfma_f32_16x16x32_bf16 v[38:41], v[170:173], v[194:197], v[38:41]
	v_mfma_f32_16x16x32_bf16 v[34:37], v[178:181], v[194:197], v[34:37]
	v_mfma_f32_16x16x32_bf16 v[22:25], v[170:173], v[202:205], v[22:25]
	v_mfma_f32_16x16x32_bf16 v[18:21], v[178:181], v[202:205], v[18:21]
	v_mfma_f32_16x16x32_bf16 v[6:9], v[170:173], v[210:213], v[6:9]
	v_mfma_f32_16x16x32_bf16 v[2:5], v[178:181], v[210:213], v[2:5]
	s_barrier
	s_setprio 1
	s_add_i32 s56, 0, 0x18000
	s_add_i32 s57, 0, 0x1c000
	v_add_u32_e32 v162, s56, v159
	v_add_u32_e32 v178, s57, v159
	ds_read_b128 v[130:133], v162
	ds_read_b128 v[134:137], v162 offset:1024
	ds_read_b128 v[148:151], v162 offset:2048
	ds_read_b128 v[162:165], v162 offset:3072
	ds_read_b128 v[166:169], v178
	ds_read_b128 v[170:173], v178 offset:1024
	ds_read_b128 v[174:177], v178 offset:2048
	ds_read_b128 v[178:181], v178 offset:3072
	s_add_u32 s26, s26, 0x100000
	s_addc_u32 s27, s27, 0
	s_mov_b32 m0, s44
	v_lshl_add_u64 v[218:219], s[26:27], 0, v[138:139]
	ds_read_b128 v[182:185], v161 offset:32768
	ds_read_b128 v[186:189], v161 offset:33792
	ds_read_b128 v[190:193], v161 offset:34816
	ds_read_b128 v[194:197], v161 offset:35840
	ds_read_b128 v[198:201], v161 offset:36864
	ds_read_b128 v[202:205], v161 offset:37888
	ds_read_b128 v[206:209], v161 offset:38912
	ds_read_b128 v[210:213], v161 offset:39936
	global_load_lds_dwordx4 v[218:219], off
	v_lshl_add_u64 v[218:219], s[26:27], 0, v[140:141]
	s_mov_b32 m0, s45
	s_nop 0
	global_load_lds_dwordx4 v[218:219], off
	s_waitcnt vmcnt(8)
	s_waitcnt lgkmcnt(0)
	s_setprio 0
	s_barrier
	s_waitcnt lgkmcnt(0)
	v_mfma_f32_16x16x32_bf16 v[126:129], v[130:133], v[182:185], v[126:129]
	v_mfma_f32_16x16x32_bf16 v[122:125], v[148:151], v[182:185], v[122:125]
	v_mfma_f32_16x16x32_bf16 v[110:113], v[130:133], v[190:193], v[110:113]
	v_mfma_f32_16x16x32_bf16 v[106:109], v[148:151], v[190:193], v[106:109]
	v_mfma_f32_16x16x32_bf16 v[94:97], v[130:133], v[198:201], v[94:97]
	v_mfma_f32_16x16x32_bf16 v[90:93], v[148:151], v[198:201], v[90:93]
	v_mfma_f32_16x16x32_bf16 v[78:81], v[130:133], v[206:209], v[78:81]
	v_mfma_f32_16x16x32_bf16 v[74:77], v[148:151], v[206:209], v[74:77]
	v_mfma_f32_16x16x32_bf16 v[126:129], v[134:137], v[186:189], v[126:129]
	v_mfma_f32_16x16x32_bf16 v[122:125], v[162:165], v[186:189], v[122:125]
	v_mfma_f32_16x16x32_bf16 v[110:113], v[134:137], v[194:197], v[110:113]
	v_mfma_f32_16x16x32_bf16 v[106:109], v[162:165], v[194:197], v[106:109]
	v_mfma_f32_16x16x32_bf16 v[94:97], v[134:137], v[202:205], v[94:97]
	v_mfma_f32_16x16x32_bf16 v[90:93], v[162:165], v[202:205], v[90:93]
	v_mfma_f32_16x16x32_bf16 v[78:81], v[134:137], v[210:213], v[78:81]
	v_mfma_f32_16x16x32_bf16 v[74:77], v[162:165], v[210:213], v[74:77]
	v_mfma_f32_16x16x32_bf16 v[118:121], v[166:169], v[182:185], v[118:121]
	v_mfma_f32_16x16x32_bf16 v[114:117], v[174:177], v[182:185], v[114:117]
	v_mfma_f32_16x16x32_bf16 v[102:105], v[166:169], v[190:193], v[102:105]
	v_mfma_f32_16x16x32_bf16 v[98:101], v[174:177], v[190:193], v[98:101]
	v_mfma_f32_16x16x32_bf16 v[86:89], v[166:169], v[198:201], v[86:89]
	v_mfma_f32_16x16x32_bf16 v[82:85], v[174:177], v[198:201], v[82:85]
	v_mfma_f32_16x16x32_bf16 v[70:73], v[166:169], v[206:209], v[70:73]
	v_mfma_f32_16x16x32_bf16 v[66:69], v[174:177], v[206:209], v[66:69]
	v_mfma_f32_16x16x32_bf16 v[118:121], v[170:173], v[186:189], v[118:121]
	v_mfma_f32_16x16x32_bf16 v[114:117], v[178:181], v[186:189], v[114:117]
	v_mfma_f32_16x16x32_bf16 v[102:105], v[170:173], v[194:197], v[102:105]
	v_mfma_f32_16x16x32_bf16 v[98:101], v[178:181], v[194:197], v[98:101]
	v_mfma_f32_16x16x32_bf16 v[86:89], v[170:173], v[202:205], v[86:89]
	v_mfma_f32_16x16x32_bf16 v[82:85], v[178:181], v[202:205], v[82:85]
	v_mfma_f32_16x16x32_bf16 v[70:73], v[170:173], v[210:213], v[70:73]
	v_mfma_f32_16x16x32_bf16 v[66:69], v[178:181], v[210:213], v[66:69]
	s_barrier
	s_setprio 1
	s_add_i32 s26, s56, s37
	v_lshl_add_u64 v[152:153], v[152:153], 0, s[62:63]
	s_mov_b32 m0, s26
	ds_read_b128 v[182:185], v161 offset:49152
	ds_read_b128 v[186:189], v161 offset:50176
	ds_read_b128 v[190:193], v161 offset:51200
	ds_read_b128 v[194:197], v161 offset:52224
	ds_read_b128 v[198:201], v161 offset:53248
	ds_read_b128 v[202:205], v161 offset:54272
	ds_read_b128 v[206:209], v161 offset:55296
	ds_read_b128 v[210:213], v161 offset:56320
	global_load_lds_dwordx4 v[152:153], off
	s_add_i32 m0, s26, 0x2000
	s_add_u32 s24, s24, 0x100080
	v_lshl_add_u64 v[152:153], v[156:157], 0, s[62:63]
	s_addc_u32 s25, s25, 0
	s_add_i32 s26, s57, s37
	global_load_lds_dwordx4 v[152:153], off
	v_lshl_add_u64 v[152:153], s[24:25], 0, v[154:155]
	s_mov_b32 m0, s26
	s_nop 0
	global_load_lds_dwordx4 v[152:153], off
	v_lshl_add_u64 v[152:153], s[24:25], 0, v[142:143]
	s_add_i32 m0, s26, 0x2000
	s_nop 0
	global_load_lds_dwordx4 v[152:153], off
	v_lshl_add_u64 v[152:153], v[214:215], 0, s[62:63]
	s_mov_b32 m0, s53
	s_nop 0
	global_load_lds_dwordx4 v[152:153], off
	v_lshl_add_u64 v[152:153], v[216:217], 0, s[62:63]
	s_mov_b32 m0, s55
	s_nop 0
	global_load_lds_dwordx4 v[152:153], off
	s_waitcnt vmcnt(8)
	s_waitcnt lgkmcnt(0)
	s_setprio 0
	s_barrier
	s_waitcnt lgkmcnt(0)
	v_mfma_f32_16x16x32_bf16 v[62:65], v[130:133], v[182:185], v[62:65]
	v_mfma_f32_16x16x32_bf16 v[58:61], v[148:151], v[182:185], v[58:61]
	v_mfma_f32_16x16x32_bf16 v[46:49], v[130:133], v[190:193], v[46:49]
	v_mfma_f32_16x16x32_bf16 v[42:45], v[148:151], v[190:193], v[42:45]
	v_mfma_f32_16x16x32_bf16 v[30:33], v[130:133], v[198:201], v[30:33]
	v_mfma_f32_16x16x32_bf16 v[26:29], v[148:151], v[198:201], v[26:29]
	v_mfma_f32_16x16x32_bf16 v[14:17], v[130:133], v[206:209], v[14:17]
	v_mfma_f32_16x16x32_bf16 v[10:13], v[148:151], v[206:209], v[10:13]
	v_mfma_f32_16x16x32_bf16 v[62:65], v[134:137], v[186:189], v[62:65]
	v_mfma_f32_16x16x32_bf16 v[58:61], v[162:165], v[186:189], v[58:61]
	v_mfma_f32_16x16x32_bf16 v[46:49], v[134:137], v[194:197], v[46:49]
	v_mfma_f32_16x16x32_bf16 v[42:45], v[162:165], v[194:197], v[42:45]
	v_mfma_f32_16x16x32_bf16 v[30:33], v[134:137], v[202:205], v[30:33]
	v_mfma_f32_16x16x32_bf16 v[26:29], v[162:165], v[202:205], v[26:29]
	v_mfma_f32_16x16x32_bf16 v[14:17], v[134:137], v[210:213], v[14:17]
	v_mfma_f32_16x16x32_bf16 v[10:13], v[162:165], v[210:213], v[10:13]
	v_mfma_f32_16x16x32_bf16 v[54:57], v[166:169], v[182:185], v[54:57]
	v_mfma_f32_16x16x32_bf16 v[50:53], v[174:177], v[182:185], v[50:53]
	v_mfma_f32_16x16x32_bf16 v[38:41], v[166:169], v[190:193], v[38:41]
	v_mfma_f32_16x16x32_bf16 v[34:37], v[174:177], v[190:193], v[34:37]
	v_mfma_f32_16x16x32_bf16 v[22:25], v[166:169], v[198:201], v[22:25]
	v_mfma_f32_16x16x32_bf16 v[18:21], v[174:177], v[198:201], v[18:21]
	v_mfma_f32_16x16x32_bf16 v[6:9], v[166:169], v[206:209], v[6:9]
	v_mfma_f32_16x16x32_bf16 v[2:5], v[174:177], v[206:209], v[2:5]
	v_mfma_f32_16x16x32_bf16 v[54:57], v[170:173], v[186:189], v[54:57]
	v_mfma_f32_16x16x32_bf16 v[50:53], v[178:181], v[186:189], v[50:53]
	v_mfma_f32_16x16x32_bf16 v[38:41], v[170:173], v[194:197], v[38:41]
	v_mfma_f32_16x16x32_bf16 v[34:37], v[178:181], v[194:197], v[34:37]
	v_mfma_f32_16x16x32_bf16 v[22:25], v[170:173], v[202:205], v[22:25]
	v_mfma_f32_16x16x32_bf16 v[18:21], v[178:181], v[202:205], v[18:21]
	v_mfma_f32_16x16x32_bf16 v[6:9], v[170:173], v[210:213], v[6:9]
	v_mfma_f32_16x16x32_bf16 v[2:5], v[178:181], v[210:213], v[2:5]
	s_barrier
	s_add_i32 s69, s69, 2
	s_add_u32 s22, s22, 0x100
	s_addc_u32 s23, s23, 0
	s_add_u32 s40, s40, 0x100
	s_addc_u32 s68, s68, 0
	s_cmp_gt_u32 s69, 61
	s_cbranch_scc0 .LBB0_534
	v_lshl_add_u32 v148, s20, 8, v158
	v_lshl_or_b32 v150, s18, 8, v160
	v_ashrrev_i32_e32 v149, 31, v148
	v_lshlrev_b64 v[130:131], 11, v[148:149]
	v_ashrrev_i32_e32 v151, 31, v150
	v_lshl_add_u64 v[130:131], s[8:9], 0, v[130:131]
	v_lshlrev_b64 v[132:133], 1, v[150:151]
	v_lshl_add_u64 v[172:173], v[130:131], 0, v[132:133]
	global_load_dwordx4 v[164:167], v[172:173], off
	global_load_dwordx4 v[168:171], v[172:173], off offset:256
	v_or_b32_e32 v152, 16, v148
	v_ashrrev_i32_e32 v153, 31, v152
	v_lshlrev_b64 v[130:131], 11, v[152:153]
	v_lshl_add_u64 v[130:131], s[8:9], 0, v[130:131]
	v_lshl_add_u64 v[156:157], v[130:131], 0, v[132:133]
	global_load_dwordx4 v[134:137], v[156:157], off
	global_load_dwordx4 v[130:133], v[156:157], off offset:256
	v_and_b32_e32 v163, 64, v1
	v_xor_b32_e32 v162, 16, v1
	v_add_u32_e32 v163, 64, v163
	v_xor_b32_e32 v174, 32, v1
	v_cmp_lt_i32_e32 vcc, v162, v163
	s_lshl_b32 s18, s18, 2
	s_ashr_i32 s19, s18, 31
	v_cndmask_b32_e32 v162, v1, v162, vcc
	v_cmp_lt_i32_e32 vcc, v174, v163
	v_lshlrev_b32_e32 v162, 2, v162
	s_waitcnt vmcnt(0)
	v_and_b32_e32 v175, 0xffff0000, v164
	v_cndmask_b32_e32 v163, v1, v174, vcc
	v_lshlrev_b32_e32 v174, 16, v164
	v_lshlrev_b32_e32 v164, 16, v165
	v_and_b32_e32 v165, 0xffff0000, v165
	v_lshlrev_b32_e32 v176, 16, v166
	v_and_b32_e32 v177, 0xffff0000, v166
	v_lshlrev_b32_e32 v166, 16, v167
	v_and_b32_e32 v167, 0xffff0000, v167
	v_lshlrev_b32_e32 v178, 16, v168
	v_and_b32_e32 v179, 0xffff0000, v168
	v_lshlrev_b32_e32 v168, 16, v169
	v_and_b32_e32 v169, 0xffff0000, v169
	v_lshlrev_b32_e32 v180, 16, v170
	v_and_b32_e32 v181, 0xffff0000, v170
	v_lshlrev_b32_e32 v170, 16, v171
	v_and_b32_e32 v171, 0xffff0000, v171
	v_pk_add_f32 v[128:129], v[128:129], v[164:165]
	v_pk_add_f32 v[126:127], v[126:127], v[174:175]
	v_pk_add_f32 v[122:123], v[122:123], v[176:177]
	v_pk_add_f32 v[124:125], v[124:125], v[166:167]
	v_pk_add_f32 v[120:121], v[120:121], v[168:169]
	v_pk_add_f32 v[118:119], v[118:119], v[178:179]
	v_pk_add_f32 v[164:165], v[114:115], v[180:181]
	v_pk_add_f32 v[166:167], v[116:117], v[170:171]
	v_cvt_pk_bf16_f32 v114, v126, v127
	v_cvt_pk_bf16_f32 v115, v128, v129
	v_mul_f32_e32 v116, v126, v126
	v_mul_f32_e32 v117, v128, v128
	v_mul_f32_e32 v126, v122, v122
	v_mul_f32_e32 v128, v125, v125
	v_mul_f32_e32 v168, v118, v118
	v_mul_f32_e32 v169, v120, v120
	v_mul_f32_e32 v170, v164, v164
	v_mul_f32_e32 v171, v167, v167
	v_fmac_f32_e32 v116, v127, v127
	v_fmac_f32_e32 v117, v129, v129
	v_fmac_f32_e32 v126, v123, v123
	v_fmac_f32_e32 v128, v124, v124
	v_fmac_f32_e32 v168, v119, v119
	v_fmac_f32_e32 v169, v121, v121
	v_fmac_f32_e32 v170, v165, v165
	v_fmac_f32_e32 v171, v166, v166
	v_add_f32_e32 v116, v117, v116
	v_add_f32_e32 v117, v128, v126
	v_add_f32_e32 v126, v169, v168
	v_add_f32_e32 v127, v171, v170
	v_add_f32_e32 v116, v117, v116
	v_add_f32_e32 v117, v127, v126
	v_add_f32_e32 v126, v116, v117
	ds_bpermute_b32 v127, v162, v126
	v_cvt_pk_bf16_f32 v116, v122, v123
	v_cvt_pk_bf16_f32 v117, v124, v125
	global_store_dwordx4 v[172:173], v[114:117], off
	s_waitcnt lgkmcnt(0)
	s_nop 0
	v_add_f32_e32 v114, v126, v127
	v_lshlrev_b32_e32 v126, 2, v163
	ds_bpermute_b32 v115, v126, v114
	v_cvt_pk_bf16_f32 v116, v118, v119
	v_cvt_pk_bf16_f32 v117, v120, v121
	v_cvt_pk_bf16_f32 v118, v164, v165
	v_cvt_pk_bf16_f32 v119, v166, v167
	global_store_dwordx4 v[172:173], v[116:119], off offset:256
	s_and_saveexec_b64 s[20:21], s[0:1]
	s_cbranch_execz .LBB0_537
	v_lshlrev_b64 v[116:117], 7, v[148:149]
	v_lshl_add_u64 v[116:117], s[6:7], 0, v[116:117]
	v_lshl_add_u64 v[116:117], s[18:19], 2, v[116:117]
	s_lshl_b32 s40, s51, 2
	v_lshl_add_u64 v[116:117], v[116:117], 0, s[40:41]
	s_waitcnt lgkmcnt(0)
	v_add_f32_e32 v114, v114, v115
	global_store_dword v[116:117], v114, off

.LBB0_631:
	s_setprio 1
	s_add_u32 s28, s26, 0xfffc0080
	s_addc_u32 s29, s27, -1
	s_add_i32 s62, 0, 0x10000
	s_cmp_eq_u32 s61, 12
	s_cselect_b32 s31, s3, s29
	s_cselect_b32 s30, s19, s28
	s_cselect_b32 s29, s17, s60
	s_cselect_b32 s28, s58, s59
	s_add_i32 s64, 0, 0x14000
	v_add_u32_e32 v142, s62, v246
	v_add_u32_e32 v158, s64, v246
	ds_read_b128 v[130:133], v142
	ds_read_b128 v[134:137], v142 offset:1024
	ds_read_b128 v[138:141], v142 offset:2048
	ds_read_b128 v[142:145], v142 offset:3072
	ds_read_b128 v[146:149], v158
	ds_read_b128 v[150:153], v158 offset:1024
	ds_read_b128 v[154:157], v158 offset:2048
	ds_read_b128 v[158:161], v158 offset:3072
	v_lshl_add_u64 v[192:193], s[26:27], 0, v[184:185]
	s_add_i32 m0, s25, 0xc000
	ds_read_b128 v[162:165], v247
	ds_read_b128 v[188:191], v247 offset:1024
	ds_read_b128 v[202:205], v247 offset:2048
	ds_read_b128 v[206:209], v247 offset:3072
	ds_read_b128 v[210:213], v247 offset:4096
	ds_read_b128 v[214:217], v247 offset:5120
	ds_read_b128 v[218:221], v247 offset:6144
	ds_read_b128 v[222:225], v247 offset:7168
	global_load_lds_dwordx4 v[192:193], off
	v_lshl_add_u64 v[192:193], s[26:27], 0, v[186:187]
	s_add_i32 m0, s25, 0xe000
	s_nop 0
	global_load_lds_dwordx4 v[192:193], off
	s_waitcnt vmcnt(8)
	s_waitcnt lgkmcnt(0)
	s_setprio 0
	s_barrier
	s_waitcnt lgkmcnt(0)
	v_mfma_f32_16x16x32_bf16 v[126:129], v[130:133], v[162:165], v[126:129]
	v_mfma_f32_16x16x32_bf16 v[122:125], v[138:141], v[162:165], v[122:125]
	v_mfma_f32_16x16x32_bf16 v[110:113], v[130:133], v[202:205], v[110:113]
	v_mfma_f32_16x16x32_bf16 v[106:109], v[138:141], v[202:205], v[106:109]
	v_mfma_f32_16x16x32_bf16 v[94:97], v[130:133], v[210:213], v[94:97]
	v_mfma_f32_16x16x32_bf16 v[90:93], v[138:141], v[210:213], v[90:93]
	v_mfma_f32_16x16x32_bf16 v[78:81], v[130:133], v[218:221], v[78:81]
	v_mfma_f32_16x16x32_bf16 v[74:77], v[138:141], v[218:221], v[74:77]
	v_mfma_f32_16x16x32_bf16 v[126:129], v[134:137], v[188:191], v[126:129]
	v_mfma_f32_16x16x32_bf16 v[122:125], v[142:145], v[188:191], v[122:125]
	v_mfma_f32_16x16x32_bf16 v[110:113], v[134:137], v[206:209], v[110:113]
	v_mfma_f32_16x16x32_bf16 v[106:109], v[142:145], v[206:209], v[106:109]
	v_mfma_f32_16x16x32_bf16 v[94:97], v[134:137], v[214:217], v[94:97]
	v_mfma_f32_16x16x32_bf16 v[90:93], v[142:145], v[214:217], v[90:93]
	v_mfma_f32_16x16x32_bf16 v[78:81], v[134:137], v[222:225], v[78:81]
	v_mfma_f32_16x16x32_bf16 v[74:77], v[142:145], v[222:225], v[74:77]
	v_mfma_f32_16x16x32_bf16 v[118:121], v[146:149], v[162:165], v[118:121]
	v_mfma_f32_16x16x32_bf16 v[114:117], v[154:157], v[162:165], v[114:117]
	v_mfma_f32_16x16x32_bf16 v[102:105], v[146:149], v[202:205], v[102:105]
	v_mfma_f32_16x16x32_bf16 v[98:101], v[154:157], v[202:205], v[98:101]
	v_mfma_f32_16x16x32_bf16 v[86:89], v[146:149], v[210:213], v[86:89]
	v_mfma_f32_16x16x32_bf16 v[82:85], v[154:157], v[210:213], v[82:85]
	v_mfma_f32_16x16x32_bf16 v[70:73], v[146:149], v[218:221], v[70:73]
	v_mfma_f32_16x16x32_bf16 v[66:69], v[154:157], v[218:221], v[66:69]
	v_mfma_f32_16x16x32_bf16 v[118:121], v[150:153], v[188:191], v[118:121]
	v_mfma_f32_16x16x32_bf16 v[114:117], v[158:161], v[188:191], v[114:117]
	v_mfma_f32_16x16x32_bf16 v[102:105], v[150:153], v[206:209], v[102:105]
	v_mfma_f32_16x16x32_bf16 v[98:101], v[158:161], v[206:209], v[98:101]
	v_mfma_f32_16x16x32_bf16 v[86:89], v[150:153], v[214:217], v[86:89]
	v_mfma_f32_16x16x32_bf16 v[82:85], v[158:161], v[214:217], v[82:85]
	v_mfma_f32_16x16x32_bf16 v[70:73], v[150:153], v[222:225], v[70:73]
	v_mfma_f32_16x16x32_bf16 v[66:69], v[158:161], v[222:225], v[66:69]
	s_barrier
	s_setprio 1
	s_add_i32 s62, s62, s45
	v_lshl_add_u64 v[192:193], s[28:29], 0, v[168:169]
	s_mov_b32 m0, s62
	ds_read_b128 v[162:165], v247 offset:16384
	ds_read_b128 v[188:191], v247 offset:17408
	ds_read_b128 v[202:205], v247 offset:18432
	ds_read_b128 v[206:209], v247 offset:19456
	ds_read_b128 v[210:213], v247 offset:20480
	ds_read_b128 v[214:217], v247 offset:21504
	ds_read_b128 v[218:221], v247 offset:22528
	ds_read_b128 v[222:225], v247 offset:23552
	global_load_lds_dwordx4 v[192:193], off
	s_add_i32 m0, s62, 0x2000
	s_add_u32 s62, s28, 0x40000
	v_lshl_add_u64 v[226:227], s[28:29], 0, v[172:173]
	s_addc_u32 s63, s29, 0
	s_add_i32 s64, s64, s45
	global_load_lds_dwordx4 v[226:227], off
	v_lshl_add_u64 v[228:229], s[62:63], 0, v[168:169]
	s_mov_b32 m0, s64
	v_lshl_add_u64 v[248:249], s[30:31], 0, v[170:171]
	global_load_lds_dwordx4 v[228:229], off
	v_lshl_add_u64 v[228:229], s[62:63], 0, v[172:173]
	s_add_i32 m0, s64, 0x2000
	s_nop 0
	global_load_lds_dwordx4 v[228:229], off
	v_lshl_add_u64 v[228:229], s[30:31], 0, v[166:167]
	s_mov_b32 m0, s25
	s_nop 0
	global_load_lds_dwordx4 v[228:229], off
	s_mov_b32 m0, s46
	s_nop 0
	global_load_lds_dwordx4 v[248:249], off
	s_waitcnt vmcnt(8)
	s_waitcnt lgkmcnt(0)
	s_setprio 0
	s_barrier
	s_waitcnt lgkmcnt(0)
	v_mfma_f32_16x16x32_bf16 v[62:65], v[130:133], v[162:165], v[62:65]
	v_mfma_f32_16x16x32_bf16 v[58:61], v[138:141], v[162:165], v[58:61]
	v_mfma_f32_16x16x32_bf16 v[46:49], v[130:133], v[202:205], v[46:49]
	v_mfma_f32_16x16x32_bf16 v[42:45], v[138:141], v[202:205], v[42:45]
	v_mfma_f32_16x16x32_bf16 v[30:33], v[130:133], v[210:213], v[30:33]
	v_mfma_f32_16x16x32_bf16 v[26:29], v[138:141], v[210:213], v[26:29]
	v_mfma_f32_16x16x32_bf16 v[14:17], v[130:133], v[218:221], v[14:17]
	v_mfma_f32_16x16x32_bf16 v[10:13], v[138:141], v[218:221], v[10:13]
	v_mfma_f32_16x16x32_bf16 v[62:65], v[134:137], v[188:191], v[62:65]
	v_mfma_f32_16x16x32_bf16 v[58:61], v[142:145], v[188:191], v[58:61]
	v_mfma_f32_16x16x32_bf16 v[46:49], v[134:137], v[206:209], v[46:49]
	v_mfma_f32_16x16x32_bf16 v[42:45], v[142:145], v[206:209], v[42:45]
	v_mfma_f32_16x16x32_bf16 v[30:33], v[134:137], v[214:217], v[30:33]
	v_mfma_f32_16x16x32_bf16 v[26:29], v[142:145], v[214:217], v[26:29]
	v_mfma_f32_16x16x32_bf16 v[14:17], v[134:137], v[222:225], v[14:17]
	v_mfma_f32_16x16x32_bf16 v[10:13], v[142:145], v[222:225], v[10:13]
	v_mfma_f32_16x16x32_bf16 v[54:57], v[146:149], v[162:165], v[54:57]
	v_mfma_f32_16x16x32_bf16 v[50:53], v[154:157], v[162:165], v[50:53]
	v_mfma_f32_16x16x32_bf16 v[38:41], v[146:149], v[202:205], v[38:41]
	v_mfma_f32_16x16x32_bf16 v[34:37], v[154:157], v[202:205], v[34:37]
	v_mfma_f32_16x16x32_bf16 v[22:25], v[146:149], v[210:213], v[22:25]
	v_mfma_f32_16x16x32_bf16 v[18:21], v[154:157], v[210:213], v[18:21]
	v_mfma_f32_16x16x32_bf16 v[6:9], v[146:149], v[218:221], v[6:9]
	v_mfma_f32_16x16x32_bf16 v[2:5], v[154:157], v[218:221], v[2:5]
	v_mfma_f32_16x16x32_bf16 v[54:57], v[150:153], v[188:191], v[54:57]
	v_mfma_f32_16x16x32_bf16 v[50:53], v[158:161], v[188:191], v[50:53]
	v_mfma_f32_16x16x32_bf16 v[38:41], v[150:153], v[206:209], v[38:41]
	v_mfma_f32_16x16x32_bf16 v[34:37], v[158:161], v[206:209], v[34:37]
	v_mfma_f32_16x16x32_bf16 v[22:25], v[150:153], v[214:217], v[22:25]
	v_mfma_f32_16x16x32_bf16 v[18:21], v[158:161], v[214:217], v[18:21]
	v_mfma_f32_16x16x32_bf16 v[6:9], v[150:153], v[222:225], v[6:9]
	v_mfma_f32_16x16x32_bf16 v[2:5], v[158:161], v[222:225], v[2:5]
	s_barrier
	s_setprio 1
	s_add_i32 s62, 0, 0x18000
	s_add_i32 s63, 0, 0x1c000
	v_add_u32_e32 v142, s62, v246
	v_add_u32_e32 v158, s63, v246
	ds_read_b128 v[130:133], v142
	ds_read_b128 v[134:137], v142 offset:1024
	ds_read_b128 v[138:141], v142 offset:2048
	ds_read_b128 v[142:145], v142 offset:3072
	ds_read_b128 v[146:149], v158
	ds_read_b128 v[150:153], v158 offset:1024
	ds_read_b128 v[154:157], v158 offset:2048
	ds_read_b128 v[158:161], v158 offset:3072
	s_add_u32 s30, s30, 0x40000
	s_addc_u32 s31, s31, 0
	s_mov_b32 m0, s47
	v_lshl_add_u64 v[250:251], s[30:31], 0, v[166:167]
	ds_read_b128 v[162:165], v247 offset:32768
	ds_read_b128 v[188:191], v247 offset:33792
	ds_read_b128 v[202:205], v247 offset:34816
	ds_read_b128 v[206:209], v247 offset:35840
	ds_read_b128 v[210:213], v247 offset:36864
	ds_read_b128 v[214:217], v247 offset:37888
	ds_read_b128 v[218:221], v247 offset:38912
	ds_read_b128 v[222:225], v247 offset:39936
	global_load_lds_dwordx4 v[250:251], off
	v_lshl_add_u64 v[250:251], s[30:31], 0, v[170:171]
	s_mov_b32 m0, s48
	s_nop 0
	global_load_lds_dwordx4 v[250:251], off
	s_waitcnt vmcnt(8)
	s_waitcnt lgkmcnt(0)
	s_setprio 0
	s_barrier
	s_waitcnt lgkmcnt(0)
	v_mfma_f32_16x16x32_bf16 v[126:129], v[130:133], v[162:165], v[126:129]
	v_mfma_f32_16x16x32_bf16 v[122:125], v[138:141], v[162:165], v[122:125]
	v_mfma_f32_16x16x32_bf16 v[110:113], v[130:133], v[202:205], v[110:113]
	v_mfma_f32_16x16x32_bf16 v[106:109], v[138:141], v[202:205], v[106:109]
	v_mfma_f32_16x16x32_bf16 v[94:97], v[130:133], v[210:213], v[94:97]
	v_mfma_f32_16x16x32_bf16 v[90:93], v[138:141], v[210:213], v[90:93]
	v_mfma_f32_16x16x32_bf16 v[78:81], v[130:133], v[218:221], v[78:81]
	v_mfma_f32_16x16x32_bf16 v[74:77], v[138:141], v[218:221], v[74:77]
	v_mfma_f32_16x16x32_bf16 v[126:129], v[134:137], v[188:191], v[126:129]
	v_mfma_f32_16x16x32_bf16 v[122:125], v[142:145], v[188:191], v[122:125]
	v_mfma_f32_16x16x32_bf16 v[110:113], v[134:137], v[206:209], v[110:113]
	v_mfma_f32_16x16x32_bf16 v[106:109], v[142:145], v[206:209], v[106:109]
	v_mfma_f32_16x16x32_bf16 v[94:97], v[134:137], v[214:217], v[94:97]
	v_mfma_f32_16x16x32_bf16 v[90:93], v[142:145], v[214:217], v[90:93]
	v_mfma_f32_16x16x32_bf16 v[78:81], v[134:137], v[222:225], v[78:81]
	v_mfma_f32_16x16x32_bf16 v[74:77], v[142:145], v[222:225], v[74:77]
	v_mfma_f32_16x16x32_bf16 v[118:121], v[146:149], v[162:165], v[118:121]
	v_mfma_f32_16x16x32_bf16 v[114:117], v[154:157], v[162:165], v[114:117]
	v_mfma_f32_16x16x32_bf16 v[102:105], v[146:149], v[202:205], v[102:105]
	v_mfma_f32_16x16x32_bf16 v[98:101], v[154:157], v[202:205], v[98:101]
	v_mfma_f32_16x16x32_bf16 v[86:89], v[146:149], v[210:213], v[86:89]
	v_mfma_f32_16x16x32_bf16 v[82:85], v[154:157], v[210:213], v[82:85]
	v_mfma_f32_16x16x32_bf16 v[70:73], v[146:149], v[218:221], v[70:73]
	v_mfma_f32_16x16x32_bf16 v[66:69], v[154:157], v[218:221], v[66:69]
	v_mfma_f32_16x16x32_bf16 v[118:121], v[150:153], v[188:191], v[118:121]
	v_mfma_f32_16x16x32_bf16 v[114:117], v[158:161], v[188:191], v[114:117]
	v_mfma_f32_16x16x32_bf16 v[102:105], v[150:153], v[206:209], v[102:105]
	v_mfma_f32_16x16x32_bf16 v[98:101], v[158:161], v[206:209], v[98:101]
	v_mfma_f32_16x16x32_bf16 v[86:89], v[150:153], v[214:217], v[86:89]
	v_mfma_f32_16x16x32_bf16 v[82:85], v[158:161], v[214:217], v[82:85]
	v_mfma_f32_16x16x32_bf16 v[70:73], v[150:153], v[222:225], v[70:73]
	v_mfma_f32_16x16x32_bf16 v[66:69], v[158:161], v[222:225], v[66:69]
	s_barrier
	s_setprio 1
	s_add_i32 s30, s62, s45
	v_lshl_add_u64 v[192:193], v[192:193], 0, s[92:93]
	s_mov_b32 m0, s30
	ds_read_b128 v[162:165], v247 offset:49152
	ds_read_b128 v[188:191], v247 offset:50176
	ds_read_b128 v[202:205], v247 offset:51200
	ds_read_b128 v[206:209], v247 offset:52224
	ds_read_b128 v[210:213], v247 offset:53248
	ds_read_b128 v[214:217], v247 offset:54272
	ds_read_b128 v[218:221], v247 offset:55296
	ds_read_b128 v[222:225], v247 offset:56320
	global_load_lds_dwordx4 v[192:193], off
	s_add_i32 m0, s30, 0x2000
	s_add_u32 s28, s28, 0x40080
	v_lshl_add_u64 v[192:193], v[226:227], 0, s[92:93]
	s_addc_u32 s29, s29, 0
	s_add_i32 s30, s63, s45
	global_load_lds_dwordx4 v[192:193], off
	v_lshl_add_u64 v[192:193], s[28:29], 0, v[168:169]
	s_mov_b32 m0, s30
	s_nop 0
	global_load_lds_dwordx4 v[192:193], off
	v_lshl_add_u64 v[192:193], s[28:29], 0, v[172:173]
	s_add_i32 m0, s30, 0x2000
	s_nop 0
	global_load_lds_dwordx4 v[192:193], off
	v_lshl_add_u64 v[192:193], v[228:229], 0, s[92:93]
	s_mov_b32 m0, s52
	s_nop 0
	global_load_lds_dwordx4 v[192:193], off
	v_lshl_add_u64 v[192:193], v[248:249], 0, s[92:93]
	s_mov_b32 m0, s53
	s_nop 0
	global_load_lds_dwordx4 v[192:193], off
	s_waitcnt vmcnt(8)
	s_waitcnt lgkmcnt(0)
	s_setprio 0
	s_barrier
	s_waitcnt lgkmcnt(0)
	v_mfma_f32_16x16x32_bf16 v[62:65], v[130:133], v[162:165], v[62:65]
	v_mfma_f32_16x16x32_bf16 v[58:61], v[138:141], v[162:165], v[58:61]
	v_mfma_f32_16x16x32_bf16 v[46:49], v[130:133], v[202:205], v[46:49]
	v_mfma_f32_16x16x32_bf16 v[42:45], v[138:141], v[202:205], v[42:45]
	v_mfma_f32_16x16x32_bf16 v[30:33], v[130:133], v[210:213], v[30:33]
	v_mfma_f32_16x16x32_bf16 v[26:29], v[138:141], v[210:213], v[26:29]
	v_mfma_f32_16x16x32_bf16 v[14:17], v[130:133], v[218:221], v[14:17]
	v_mfma_f32_16x16x32_bf16 v[10:13], v[138:141], v[218:221], v[10:13]
	v_mfma_f32_16x16x32_bf16 v[62:65], v[134:137], v[188:191], v[62:65]
	v_mfma_f32_16x16x32_bf16 v[58:61], v[142:145], v[188:191], v[58:61]
	v_mfma_f32_16x16x32_bf16 v[46:49], v[134:137], v[206:209], v[46:49]
	v_mfma_f32_16x16x32_bf16 v[42:45], v[142:145], v[206:209], v[42:45]
	v_mfma_f32_16x16x32_bf16 v[30:33], v[134:137], v[214:217], v[30:33]
	v_mfma_f32_16x16x32_bf16 v[26:29], v[142:145], v[214:217], v[26:29]
	v_mfma_f32_16x16x32_bf16 v[14:17], v[134:137], v[222:225], v[14:17]
	v_mfma_f32_16x16x32_bf16 v[10:13], v[142:145], v[222:225], v[10:13]
	v_mfma_f32_16x16x32_bf16 v[54:57], v[146:149], v[162:165], v[54:57]
	v_mfma_f32_16x16x32_bf16 v[50:53], v[154:157], v[162:165], v[50:53]
	v_mfma_f32_16x16x32_bf16 v[38:41], v[146:149], v[202:205], v[38:41]
	v_mfma_f32_16x16x32_bf16 v[34:37], v[154:157], v[202:205], v[34:37]
	v_mfma_f32_16x16x32_bf16 v[22:25], v[146:149], v[210:213], v[22:25]
	v_mfma_f32_16x16x32_bf16 v[18:21], v[154:157], v[210:213], v[18:21]
	v_mfma_f32_16x16x32_bf16 v[6:9], v[146:149], v[218:221], v[6:9]
	v_mfma_f32_16x16x32_bf16 v[2:5], v[154:157], v[218:221], v[2:5]
	v_mfma_f32_16x16x32_bf16 v[54:57], v[150:153], v[188:191], v[54:57]
	v_mfma_f32_16x16x32_bf16 v[50:53], v[158:161], v[188:191], v[50:53]
	v_mfma_f32_16x16x32_bf16 v[38:41], v[150:153], v[206:209], v[38:41]
	v_mfma_f32_16x16x32_bf16 v[34:37], v[158:161], v[206:209], v[34:37]
	v_mfma_f32_16x16x32_bf16 v[22:25], v[150:153], v[214:217], v[22:25]
	v_mfma_f32_16x16x32_bf16 v[18:21], v[158:161], v[214:217], v[18:21]
	v_mfma_f32_16x16x32_bf16 v[6:9], v[150:153], v[222:225], v[6:9]
	v_mfma_f32_16x16x32_bf16 v[2:5], v[158:161], v[222:225], v[2:5]
	s_barrier
	s_add_i32 s61, s61, 2
	s_add_u32 s26, s26, 0x100
	s_addc_u32 s27, s27, 0
	s_add_u32 s59, s59, 0x100
	s_addc_u32 s60, s60, 0
	s_cmp_gt_u32 s61, 13
	s_cbranch_scc0 .LBB0_631
	s_and_b64 vcc, exec, s[14:15]
	s_cbranch_vccnz .LBB0_636
	s_cmp_gt_i32 s2, 4
	s_mov_b64 s[26:27], -1
	s_cbranch_scc0 .LBB0_637

.LBB0_939:
	s_setprio 1
	s_add_u32 s24, s22, 0xfffc0080
	s_addc_u32 s25, s23, -1
	s_add_i32 s52, 0, 0x10000
	s_cmp_eq_u32 s51, 12
	s_cselect_b32 s27, s13, s25
	s_cselect_b32 s26, s19, s24
	s_cselect_b32 s25, s11, s50
	s_cselect_b32 s24, s21, s49
	s_add_i32 s54, 0, 0x14000
	v_add_u32_e32 v142, s52, v167
	v_add_u32_e32 v164, s54, v167
	ds_read_b128 v[130:133], v142
	ds_read_b128 v[134:137], v142 offset:1024
	ds_read_b128 v[138:141], v142 offset:2048
	ds_read_b128 v[142:145], v142 offset:3072
	ds_read_b128 v[156:159], v164
	ds_read_b128 v[160:163], v164 offset:1024
	ds_read_b128 v[170:173], v164 offset:2048
	ds_read_b128 v[174:177], v164 offset:3072
	v_lshl_add_u64 v[164:165], s[22:23], 0, v[152:153]
	s_add_i32 m0, s38, 0xc000
	ds_read_b128 v[178:181], v169
	ds_read_b128 v[182:185], v169 offset:1024
	ds_read_b128 v[186:189], v169 offset:2048
	ds_read_b128 v[190:193], v169 offset:3072
	ds_read_b128 v[202:205], v169 offset:4096
	ds_read_b128 v[206:209], v169 offset:5120
	ds_read_b128 v[210:213], v169 offset:6144
	ds_read_b128 v[214:217], v169 offset:7168
	global_load_lds_dwordx4 v[164:165], off
	v_lshl_add_u64 v[164:165], s[22:23], 0, v[154:155]
	s_add_i32 m0, s38, 0xe000
	s_nop 0
	global_load_lds_dwordx4 v[164:165], off
	s_waitcnt vmcnt(8)
	s_waitcnt lgkmcnt(0)
	s_setprio 0
	s_barrier
	s_waitcnt lgkmcnt(0)
	v_mfma_f32_16x16x32_bf16 v[126:129], v[130:133], v[178:181], v[126:129]
	v_mfma_f32_16x16x32_bf16 v[122:125], v[138:141], v[178:181], v[122:125]
	v_mfma_f32_16x16x32_bf16 v[110:113], v[130:133], v[186:189], v[110:113]
	v_mfma_f32_16x16x32_bf16 v[106:109], v[138:141], v[186:189], v[106:109]
	v_mfma_f32_16x16x32_bf16 v[94:97], v[130:133], v[202:205], v[94:97]
	v_mfma_f32_16x16x32_bf16 v[90:93], v[138:141], v[202:205], v[90:93]
	v_mfma_f32_16x16x32_bf16 v[78:81], v[130:133], v[210:213], v[78:81]
	v_mfma_f32_16x16x32_bf16 v[74:77], v[138:141], v[210:213], v[74:77]
	v_mfma_f32_16x16x32_bf16 v[126:129], v[134:137], v[182:185], v[126:129]
	v_mfma_f32_16x16x32_bf16 v[122:125], v[142:145], v[182:185], v[122:125]
	v_mfma_f32_16x16x32_bf16 v[110:113], v[134:137], v[190:193], v[110:113]
	v_mfma_f32_16x16x32_bf16 v[106:109], v[142:145], v[190:193], v[106:109]
	v_mfma_f32_16x16x32_bf16 v[94:97], v[134:137], v[206:209], v[94:97]
	v_mfma_f32_16x16x32_bf16 v[90:93], v[142:145], v[206:209], v[90:93]
	v_mfma_f32_16x16x32_bf16 v[78:81], v[134:137], v[214:217], v[78:81]
	v_mfma_f32_16x16x32_bf16 v[74:77], v[142:145], v[214:217], v[74:77]
	v_mfma_f32_16x16x32_bf16 v[118:121], v[156:159], v[178:181], v[118:121]
	v_mfma_f32_16x16x32_bf16 v[114:117], v[170:173], v[178:181], v[114:117]
	v_mfma_f32_16x16x32_bf16 v[102:105], v[156:159], v[186:189], v[102:105]
	v_mfma_f32_16x16x32_bf16 v[98:101], v[170:173], v[186:189], v[98:101]
	v_mfma_f32_16x16x32_bf16 v[86:89], v[156:159], v[202:205], v[86:89]
	v_mfma_f32_16x16x32_bf16 v[82:85], v[170:173], v[202:205], v[82:85]
	v_mfma_f32_16x16x32_bf16 v[70:73], v[156:159], v[210:213], v[70:73]
	v_mfma_f32_16x16x32_bf16 v[66:69], v[170:173], v[210:213], v[66:69]
	v_mfma_f32_16x16x32_bf16 v[118:121], v[160:163], v[182:185], v[118:121]
	v_mfma_f32_16x16x32_bf16 v[114:117], v[174:177], v[182:185], v[114:117]
	v_mfma_f32_16x16x32_bf16 v[102:105], v[160:163], v[190:193], v[102:105]
	v_mfma_f32_16x16x32_bf16 v[98:101], v[174:177], v[190:193], v[98:101]
	v_mfma_f32_16x16x32_bf16 v[86:89], v[160:163], v[206:209], v[86:89]
	v_mfma_f32_16x16x32_bf16 v[82:85], v[174:177], v[206:209], v[82:85]
	v_mfma_f32_16x16x32_bf16 v[70:73], v[160:163], v[214:217], v[70:73]
	v_mfma_f32_16x16x32_bf16 v[66:69], v[174:177], v[214:217], v[66:69]
	s_barrier
	s_setprio 1
	s_add_i32 s52, s52, s37
	v_lshl_add_u64 v[164:165], s[24:25], 0, v[194:195]
	s_mov_b32 m0, s52
	ds_read_b128 v[178:181], v169 offset:16384
	ds_read_b128 v[182:185], v169 offset:17408
	ds_read_b128 v[186:189], v169 offset:18432
	ds_read_b128 v[190:193], v169 offset:19456
	ds_read_b128 v[202:205], v169 offset:20480
	ds_read_b128 v[206:209], v169 offset:21504
	ds_read_b128 v[210:213], v169 offset:22528
	ds_read_b128 v[214:217], v169 offset:23552
	global_load_lds_dwordx4 v[164:165], off
	s_add_i32 m0, s52, 0x2000
	s_add_u32 s52, s24, 0x40000
	v_lshl_add_u64 v[218:219], s[24:25], 0, v[150:151]
	s_addc_u32 s53, s25, 0
	s_add_i32 s54, s54, s37
	global_load_lds_dwordx4 v[218:219], off
	v_lshl_add_u64 v[220:221], s[52:53], 0, v[194:195]
	s_mov_b32 m0, s54
	v_lshl_add_u64 v[222:223], s[26:27], 0, v[148:149]
	global_load_lds_dwordx4 v[220:221], off
	v_lshl_add_u64 v[220:221], s[52:53], 0, v[150:151]
	s_add_i32 m0, s54, 0x2000
	s_nop 0
	global_load_lds_dwordx4 v[220:221], off
	v_lshl_add_u64 v[220:221], s[26:27], 0, v[146:147]
	s_mov_b32 m0, s38
	s_nop 0
	global_load_lds_dwordx4 v[220:221], off
	s_mov_b32 m0, s39
	s_nop 0
	global_load_lds_dwordx4 v[222:223], off
	s_waitcnt vmcnt(8)
	s_waitcnt lgkmcnt(0)
	s_setprio 0
	s_barrier
	s_waitcnt lgkmcnt(0)
	v_mfma_f32_16x16x32_bf16 v[62:65], v[130:133], v[178:181], v[62:65]
	v_mfma_f32_16x16x32_bf16 v[58:61], v[138:141], v[178:181], v[58:61]
	v_mfma_f32_16x16x32_bf16 v[46:49], v[130:133], v[186:189], v[46:49]
	v_mfma_f32_16x16x32_bf16 v[42:45], v[138:141], v[186:189], v[42:45]
	v_mfma_f32_16x16x32_bf16 v[30:33], v[130:133], v[202:205], v[30:33]
	v_mfma_f32_16x16x32_bf16 v[26:29], v[138:141], v[202:205], v[26:29]
	v_mfma_f32_16x16x32_bf16 v[14:17], v[130:133], v[210:213], v[14:17]
	v_mfma_f32_16x16x32_bf16 v[10:13], v[138:141], v[210:213], v[10:13]
	v_mfma_f32_16x16x32_bf16 v[62:65], v[134:137], v[182:185], v[62:65]
	v_mfma_f32_16x16x32_bf16 v[58:61], v[142:145], v[182:185], v[58:61]
	v_mfma_f32_16x16x32_bf16 v[46:49], v[134:137], v[190:193], v[46:49]
	v_mfma_f32_16x16x32_bf16 v[42:45], v[142:145], v[190:193], v[42:45]
	v_mfma_f32_16x16x32_bf16 v[30:33], v[134:137], v[206:209], v[30:33]
	v_mfma_f32_16x16x32_bf16 v[26:29], v[142:145], v[206:209], v[26:29]
	v_mfma_f32_16x16x32_bf16 v[14:17], v[134:137], v[214:217], v[14:17]
	v_mfma_f32_16x16x32_bf16 v[10:13], v[142:145], v[214:217], v[10:13]
	v_mfma_f32_16x16x32_bf16 v[54:57], v[156:159], v[178:181], v[54:57]
	v_mfma_f32_16x16x32_bf16 v[50:53], v[170:173], v[178:181], v[50:53]
	v_mfma_f32_16x16x32_bf16 v[38:41], v[156:159], v[186:189], v[38:41]
	v_mfma_f32_16x16x32_bf16 v[34:37], v[170:173], v[186:189], v[34:37]
	v_mfma_f32_16x16x32_bf16 v[22:25], v[156:159], v[202:205], v[22:25]
	v_mfma_f32_16x16x32_bf16 v[18:21], v[170:173], v[202:205], v[18:21]
	v_mfma_f32_16x16x32_bf16 v[6:9], v[156:159], v[210:213], v[6:9]
	v_mfma_f32_16x16x32_bf16 v[2:5], v[170:173], v[210:213], v[2:5]
	v_mfma_f32_16x16x32_bf16 v[54:57], v[160:163], v[182:185], v[54:57]
	v_mfma_f32_16x16x32_bf16 v[50:53], v[174:177], v[182:185], v[50:53]
	v_mfma_f32_16x16x32_bf16 v[38:41], v[160:163], v[190:193], v[38:41]
	v_mfma_f32_16x16x32_bf16 v[34:37], v[174:177], v[190:193], v[34:37]
	v_mfma_f32_16x16x32_bf16 v[22:25], v[160:163], v[206:209], v[22:25]
	v_mfma_f32_16x16x32_bf16 v[18:21], v[174:177], v[206:209], v[18:21]
	v_mfma_f32_16x16x32_bf16 v[6:9], v[160:163], v[214:217], v[6:9]
	v_mfma_f32_16x16x32_bf16 v[2:5], v[174:177], v[214:217], v[2:5]
	s_barrier
	s_setprio 1
	s_add_i32 s52, 0, 0x18000
	s_add_i32 s53, 0, 0x1c000
	v_add_u32_e32 v142, s52, v167
	v_add_u32_e32 v174, s53, v167
	ds_read_b128 v[130:133], v142
	ds_read_b128 v[134:137], v142 offset:1024
	ds_read_b128 v[138:141], v142 offset:2048
	ds_read_b128 v[142:145], v142 offset:3072
	ds_read_b128 v[156:159], v174
	ds_read_b128 v[160:163], v174 offset:1024
	ds_read_b128 v[170:173], v174 offset:2048
	ds_read_b128 v[174:177], v174 offset:3072
	s_add_u32 s26, s26, 0x40000
	s_addc_u32 s27, s27, 0
	s_mov_b32 m0, s42
	v_lshl_add_u64 v[224:225], s[26:27], 0, v[146:147]
	ds_read_b128 v[178:181], v169 offset:32768
	ds_read_b128 v[182:185], v169 offset:33792
	ds_read_b128 v[186:189], v169 offset:34816
	ds_read_b128 v[190:193], v169 offset:35840
	ds_read_b128 v[202:205], v169 offset:36864
	ds_read_b128 v[206:209], v169 offset:37888
	ds_read_b128 v[210:213], v169 offset:38912
	ds_read_b128 v[214:217], v169 offset:39936
	global_load_lds_dwordx4 v[224:225], off
	v_lshl_add_u64 v[224:225], s[26:27], 0, v[148:149]
	s_mov_b32 m0, s43
	s_nop 0
	global_load_lds_dwordx4 v[224:225], off
	s_waitcnt vmcnt(8)
	s_waitcnt lgkmcnt(0)
	s_setprio 0
	s_barrier
	s_waitcnt lgkmcnt(0)
	v_mfma_f32_16x16x32_bf16 v[126:129], v[130:133], v[178:181], v[126:129]
	v_mfma_f32_16x16x32_bf16 v[122:125], v[138:141], v[178:181], v[122:125]
	v_mfma_f32_16x16x32_bf16 v[110:113], v[130:133], v[186:189], v[110:113]
	v_mfma_f32_16x16x32_bf16 v[106:109], v[138:141], v[186:189], v[106:109]
	v_mfma_f32_16x16x32_bf16 v[94:97], v[130:133], v[202:205], v[94:97]
	v_mfma_f32_16x16x32_bf16 v[90:93], v[138:141], v[202:205], v[90:93]
	v_mfma_f32_16x16x32_bf16 v[78:81], v[130:133], v[210:213], v[78:81]
	v_mfma_f32_16x16x32_bf16 v[74:77], v[138:141], v[210:213], v[74:77]
	v_mfma_f32_16x16x32_bf16 v[126:129], v[134:137], v[182:185], v[126:129]
	v_mfma_f32_16x16x32_bf16 v[122:125], v[142:145], v[182:185], v[122:125]
	v_mfma_f32_16x16x32_bf16 v[110:113], v[134:137], v[190:193], v[110:113]
	v_mfma_f32_16x16x32_bf16 v[106:109], v[142:145], v[190:193], v[106:109]
	v_mfma_f32_16x16x32_bf16 v[94:97], v[134:137], v[206:209], v[94:97]
	v_mfma_f32_16x16x32_bf16 v[90:93], v[142:145], v[206:209], v[90:93]
	v_mfma_f32_16x16x32_bf16 v[78:81], v[134:137], v[214:217], v[78:81]
	v_mfma_f32_16x16x32_bf16 v[74:77], v[142:145], v[214:217], v[74:77]
	v_mfma_f32_16x16x32_bf16 v[118:121], v[156:159], v[178:181], v[118:121]
	v_mfma_f32_16x16x32_bf16 v[114:117], v[170:173], v[178:181], v[114:117]
	v_mfma_f32_16x16x32_bf16 v[102:105], v[156:159], v[186:189], v[102:105]
	v_mfma_f32_16x16x32_bf16 v[98:101], v[170:173], v[186:189], v[98:101]
	v_mfma_f32_16x16x32_bf16 v[86:89], v[156:159], v[202:205], v[86:89]
	v_mfma_f32_16x16x32_bf16 v[82:85], v[170:173], v[202:205], v[82:85]
	v_mfma_f32_16x16x32_bf16 v[70:73], v[156:159], v[210:213], v[70:73]
	v_mfma_f32_16x16x32_bf16 v[66:69], v[170:173], v[210:213], v[66:69]
	v_mfma_f32_16x16x32_bf16 v[118:121], v[160:163], v[182:185], v[118:121]
	v_mfma_f32_16x16x32_bf16 v[114:117], v[174:177], v[182:185], v[114:117]
	v_mfma_f32_16x16x32_bf16 v[102:105], v[160:163], v[190:193], v[102:105]
	v_mfma_f32_16x16x32_bf16 v[98:101], v[174:177], v[190:193], v[98:101]
	v_mfma_f32_16x16x32_bf16 v[86:89], v[160:163], v[206:209], v[86:89]
	v_mfma_f32_16x16x32_bf16 v[82:85], v[174:177], v[206:209], v[82:85]
	v_mfma_f32_16x16x32_bf16 v[70:73], v[160:163], v[214:217], v[70:73]
	v_mfma_f32_16x16x32_bf16 v[66:69], v[174:177], v[214:217], v[66:69]
	s_barrier
	s_setprio 1
	s_add_i32 s26, s52, s37
	v_lshl_add_u64 v[164:165], v[164:165], 0, s[92:93]
	s_mov_b32 m0, s26
	ds_read_b128 v[178:181], v169 offset:49152
	ds_read_b128 v[182:185], v169 offset:50176
	ds_read_b128 v[186:189], v169 offset:51200
	ds_read_b128 v[190:193], v169 offset:52224
	ds_read_b128 v[202:205], v169 offset:53248
	ds_read_b128 v[206:209], v169 offset:54272
	ds_read_b128 v[210:213], v169 offset:55296
	ds_read_b128 v[214:217], v169 offset:56320
	global_load_lds_dwordx4 v[164:165], off
	s_add_i32 m0, s26, 0x2000
	s_add_u32 s24, s24, 0x40080
	v_lshl_add_u64 v[164:165], v[218:219], 0, s[92:93]
	s_addc_u32 s25, s25, 0
	s_add_i32 s26, s53, s37
	global_load_lds_dwordx4 v[164:165], off
	v_lshl_add_u64 v[164:165], s[24:25], 0, v[194:195]
	s_mov_b32 m0, s26
	s_nop 0
	global_load_lds_dwordx4 v[164:165], off
	v_lshl_add_u64 v[164:165], s[24:25], 0, v[150:151]
	s_add_i32 m0, s26, 0x2000
	s_nop 0
	global_load_lds_dwordx4 v[164:165], off
	v_lshl_add_u64 v[164:165], v[220:221], 0, s[92:93]
	s_mov_b32 m0, s45
	s_nop 0
	global_load_lds_dwordx4 v[164:165], off
	v_lshl_add_u64 v[164:165], v[222:223], 0, s[92:93]
	s_mov_b32 m0, s46
	s_nop 0
	global_load_lds_dwordx4 v[164:165], off
	s_waitcnt vmcnt(8)
	s_waitcnt lgkmcnt(0)
	s_setprio 0
	s_barrier
	s_waitcnt lgkmcnt(0)
	v_mfma_f32_16x16x32_bf16 v[62:65], v[130:133], v[178:181], v[62:65]
	v_mfma_f32_16x16x32_bf16 v[58:61], v[138:141], v[178:181], v[58:61]
	v_mfma_f32_16x16x32_bf16 v[46:49], v[130:133], v[186:189], v[46:49]
	v_mfma_f32_16x16x32_bf16 v[42:45], v[138:141], v[186:189], v[42:45]
	v_mfma_f32_16x16x32_bf16 v[30:33], v[130:133], v[202:205], v[30:33]
	v_mfma_f32_16x16x32_bf16 v[26:29], v[138:141], v[202:205], v[26:29]
	v_mfma_f32_16x16x32_bf16 v[14:17], v[130:133], v[210:213], v[14:17]
	v_mfma_f32_16x16x32_bf16 v[10:13], v[138:141], v[210:213], v[10:13]
	v_mfma_f32_16x16x32_bf16 v[62:65], v[134:137], v[182:185], v[62:65]
	v_mfma_f32_16x16x32_bf16 v[58:61], v[142:145], v[182:185], v[58:61]
	v_mfma_f32_16x16x32_bf16 v[46:49], v[134:137], v[190:193], v[46:49]
	v_mfma_f32_16x16x32_bf16 v[42:45], v[142:145], v[190:193], v[42:45]
	v_mfma_f32_16x16x32_bf16 v[30:33], v[134:137], v[206:209], v[30:33]
	v_mfma_f32_16x16x32_bf16 v[26:29], v[142:145], v[206:209], v[26:29]
	v_mfma_f32_16x16x32_bf16 v[14:17], v[134:137], v[214:217], v[14:17]
	v_mfma_f32_16x16x32_bf16 v[10:13], v[142:145], v[214:217], v[10:13]
	v_mfma_f32_16x16x32_bf16 v[54:57], v[156:159], v[178:181], v[54:57]
	v_mfma_f32_16x16x32_bf16 v[50:53], v[170:173], v[178:181], v[50:53]
	v_mfma_f32_16x16x32_bf16 v[38:41], v[156:159], v[186:189], v[38:41]
	v_mfma_f32_16x16x32_bf16 v[34:37], v[170:173], v[186:189], v[34:37]
	v_mfma_f32_16x16x32_bf16 v[22:25], v[156:159], v[202:205], v[22:25]
	v_mfma_f32_16x16x32_bf16 v[18:21], v[170:173], v[202:205], v[18:21]
	v_mfma_f32_16x16x32_bf16 v[6:9], v[156:159], v[210:213], v[6:9]
	v_mfma_f32_16x16x32_bf16 v[2:5], v[170:173], v[210:213], v[2:5]
	v_mfma_f32_16x16x32_bf16 v[54:57], v[160:163], v[182:185], v[54:57]
	v_mfma_f32_16x16x32_bf16 v[50:53], v[174:177], v[182:185], v[50:53]
	v_mfma_f32_16x16x32_bf16 v[38:41], v[160:163], v[190:193], v[38:41]
	v_mfma_f32_16x16x32_bf16 v[34:37], v[174:177], v[190:193], v[34:37]
	v_mfma_f32_16x16x32_bf16 v[22:25], v[160:163], v[206:209], v[22:25]
	v_mfma_f32_16x16x32_bf16 v[18:21], v[174:177], v[206:209], v[18:21]
	v_mfma_f32_16x16x32_bf16 v[6:9], v[160:163], v[214:217], v[6:9]
	v_mfma_f32_16x16x32_bf16 v[2:5], v[174:177], v[214:217], v[2:5]
	s_barrier
	s_add_i32 s51, s51, 2
	s_add_u32 s22, s22, 0x100
	s_addc_u32 s23, s23, 0
	s_add_u32 s49, s49, 0x100
	s_addc_u32 s50, s50, 0
	s_cmp_gt_u32 s51, 13
	s_cbranch_scc0 .LBB0_939
	v_lshl_add_u32 v156, s20, 8, v166
	v_lshl_or_b32 v158, s18, 8, v168
	v_ashrrev_i32_e32 v157, 31, v156
	v_lshlrev_b64 v[130:131], 11, v[156:157]
	v_ashrrev_i32_e32 v159, 31, v158
	v_lshl_add_u64 v[130:131], s[8:9], 0, v[130:131]
	v_lshlrev_b64 v[132:133], 1, v[158:159]
	v_lshl_add_u64 v[164:165], v[130:131], 0, v[132:133]
	global_load_dwordx4 v[142:145], v[164:165], off
	global_load_dwordx4 v[138:141], v[164:165], off offset:256
	v_or_b32_e32 v160, 16, v156
	v_ashrrev_i32_e32 v161, 31, v160
	v_lshlrev_b64 v[130:131], 11, v[160:161]
	v_lshl_add_u64 v[130:131], s[8:9], 0, v[130:131]
	v_lshl_add_u64 v[162:163], v[130:131], 0, v[132:133]
	global_load_dwordx4 v[134:137], v[162:163], off
	global_load_dwordx4 v[130:133], v[162:163], off offset:256
	v_and_b32_e32 v171, 64, v1
	v_xor_b32_e32 v170, 16, v1
	v_add_u32_e32 v171, 64, v171
	v_xor_b32_e32 v172, 32, v1
	v_cmp_lt_i32_e32 vcc, v170, v171
	s_lshl_b32 s18, s18, 2
	s_ashr_i32 s19, s18, 31
	v_cndmask_b32_e32 v170, v1, v170, vcc
	v_cmp_lt_i32_e32 vcc, v172, v171
	v_lshlrev_b32_e32 v170, 2, v170
	s_waitcnt vmcnt(0)
	v_and_b32_e32 v173, 0xffff0000, v142
	v_cndmask_b32_e32 v171, v1, v172, vcc
	v_lshlrev_b32_e32 v172, 16, v142
	v_lshlrev_b32_e32 v142, 16, v143
	v_and_b32_e32 v143, 0xffff0000, v143
	v_lshlrev_b32_e32 v174, 16, v144
	v_and_b32_e32 v175, 0xffff0000, v144
	v_lshlrev_b32_e32 v144, 16, v145
	v_and_b32_e32 v145, 0xffff0000, v145
	v_lshlrev_b32_e32 v176, 16, v138
	v_and_b32_e32 v177, 0xffff0000, v138
	v_lshlrev_b32_e32 v138, 16, v139
	v_and_b32_e32 v139, 0xffff0000, v139
	v_lshlrev_b32_e32 v178, 16, v140
	v_and_b32_e32 v179, 0xffff0000, v140
	v_lshlrev_b32_e32 v140, 16, v141
	v_and_b32_e32 v141, 0xffff0000, v141
	v_pk_add_f32 v[128:129], v[128:129], v[142:143]
	v_pk_add_f32 v[126:127], v[126:127], v[172:173]
	v_pk_add_f32 v[122:123], v[122:123], v[174:175]
	v_pk_add_f32 v[124:125], v[124:125], v[144:145]
	v_pk_add_f32 v[120:121], v[120:121], v[138:139]
	v_pk_add_f32 v[118:119], v[118:119], v[176:177]
	v_pk_add_f32 v[138:139], v[114:115], v[178:179]
	v_pk_add_f32 v[140:141], v[116:117], v[140:141]
	v_cvt_pk_bf16_f32 v114, v126, v127
	v_cvt_pk_bf16_f32 v115, v128, v129
	v_mul_f32_e32 v116, v126, v126
	v_mul_f32_e32 v117, v128, v128
	v_mul_f32_e32 v126, v122, v122
	v_mul_f32_e32 v128, v125, v125
	v_mul_f32_e32 v142, v118, v118
	v_mul_f32_e32 v143, v120, v120
	v_mul_f32_e32 v144, v138, v138
	v_mul_f32_e32 v145, v141, v141
	v_fmac_f32_e32 v116, v127, v127
	v_fmac_f32_e32 v117, v129, v129
	v_fmac_f32_e32 v126, v123, v123
	v_fmac_f32_e32 v128, v124, v124
	v_fmac_f32_e32 v142, v119, v119
	v_fmac_f32_e32 v143, v121, v121
	v_fmac_f32_e32 v144, v139, v139
	v_fmac_f32_e32 v145, v140, v140
	v_add_f32_e32 v116, v117, v116
	v_add_f32_e32 v117, v128, v126
	v_add_f32_e32 v126, v143, v142
	v_add_f32_e32 v127, v145, v144
	v_add_f32_e32 v116, v117, v116
	v_add_f32_e32 v117, v127, v126
	v_add_f32_e32 v126, v116, v117
	ds_bpermute_b32 v127, v170, v126
	v_cvt_pk_bf16_f32 v116, v122, v123
	v_cvt_pk_bf16_f32 v117, v124, v125
	global_store_dwordx4 v[164:165], v[114:117], off
	s_waitcnt lgkmcnt(0)
	s_nop 0
	v_add_f32_e32 v114, v126, v127
	v_lshlrev_b32_e32 v126, 2, v171
	ds_bpermute_b32 v115, v126, v114
	v_cvt_pk_bf16_f32 v116, v118, v119
	v_cvt_pk_bf16_f32 v117, v120, v121
	v_cvt_pk_bf16_f32 v118, v138, v139
	v_cvt_pk_bf16_f32 v119, v140, v141
	global_store_dwordx4 v[164:165], v[116:119], off offset:256
	s_and_saveexec_b64 s[20:21], s[0:1]
	s_cbranch_execz .LBB0_942
	v_lshlrev_b64 v[116:117], 7, v[156:157]
	v_lshl_add_u64 v[116:117], s[6:7], 0, v[116:117]
	v_lshl_add_u64 v[116:117], s[18:19], 2, v[116:117]
	s_lshl_b32 s94, s44, 2
	v_lshl_add_u64 v[116:117], v[116:117], 0, s[94:95]
	s_waitcnt lgkmcnt(0)
	v_add_f32_e32 v114, v114, v115
	global_store_dword v[116:117], v114, off

.LBB0_1040:
	s_setprio 1
	s_add_u32 s22, s20, 0xfffc0080
	s_addc_u32 s23, s21, -1
	s_add_i32 s51, 0, 0x10000
	s_cmp_eq_u32 s50, 12
	s_cselect_b32 s25, s13, s23
	s_cselect_b32 s24, s46, s22
	s_cselect_b32 s23, s11, s49
	s_cselect_b32 s22, s47, s48
	s_add_i32 s54, 0, 0x14000
	v_add_u32_e32 v156, s51, v145
	v_add_u32_e32 v172, s54, v145
	ds_read_b128 v[140:143], v156
	ds_read_b128 v[148:151], v156 offset:1024
	ds_read_b128 v[152:155], v156 offset:2048
	ds_read_b128 v[156:159], v156 offset:3072
	ds_read_b128 v[160:163], v172
	ds_read_b128 v[164:167], v172 offset:1024
	ds_read_b128 v[168:171], v172 offset:2048
	ds_read_b128 v[172:175], v172 offset:3072
	v_lshl_add_u64 v[192:193], s[20:21], 0, v[136:137]
	s_add_i32 m0, s19, 0xc000
	ds_read_b128 v[176:179], v147
	ds_read_b128 v[180:183], v147 offset:1024
	ds_read_b128 v[184:187], v147 offset:2048
	ds_read_b128 v[188:191], v147 offset:3072
	ds_read_b128 v[202:205], v147 offset:4096
	ds_read_b128 v[206:209], v147 offset:5120
	ds_read_b128 v[210:213], v147 offset:6144
	ds_read_b128 v[214:217], v147 offset:7168
	global_load_lds_dwordx4 v[192:193], off
	v_lshl_add_u64 v[192:193], s[20:21], 0, v[138:139]
	s_add_i32 m0, s19, 0xe000
	s_nop 0
	global_load_lds_dwordx4 v[192:193], off
	s_waitcnt vmcnt(8)
	s_waitcnt lgkmcnt(0)
	s_setprio 0
	s_barrier
	s_waitcnt lgkmcnt(0)
	v_mfma_f32_16x16x32_bf16 v[126:129], v[140:143], v[176:179], v[126:129]
	v_mfma_f32_16x16x32_bf16 v[122:125], v[152:155], v[176:179], v[122:125]
	v_mfma_f32_16x16x32_bf16 v[110:113], v[140:143], v[184:187], v[110:113]
	v_mfma_f32_16x16x32_bf16 v[106:109], v[152:155], v[184:187], v[106:109]
	v_mfma_f32_16x16x32_bf16 v[94:97], v[140:143], v[202:205], v[94:97]
	v_mfma_f32_16x16x32_bf16 v[90:93], v[152:155], v[202:205], v[90:93]
	v_mfma_f32_16x16x32_bf16 v[78:81], v[140:143], v[210:213], v[78:81]
	v_mfma_f32_16x16x32_bf16 v[74:77], v[152:155], v[210:213], v[74:77]
	v_mfma_f32_16x16x32_bf16 v[126:129], v[148:151], v[180:183], v[126:129]
	v_mfma_f32_16x16x32_bf16 v[122:125], v[156:159], v[180:183], v[122:125]
	v_mfma_f32_16x16x32_bf16 v[110:113], v[148:151], v[188:191], v[110:113]
	v_mfma_f32_16x16x32_bf16 v[106:109], v[156:159], v[188:191], v[106:109]
	v_mfma_f32_16x16x32_bf16 v[94:97], v[148:151], v[206:209], v[94:97]
	v_mfma_f32_16x16x32_bf16 v[90:93], v[156:159], v[206:209], v[90:93]
	v_mfma_f32_16x16x32_bf16 v[78:81], v[148:151], v[214:217], v[78:81]
	v_mfma_f32_16x16x32_bf16 v[74:77], v[156:159], v[214:217], v[74:77]
	v_mfma_f32_16x16x32_bf16 v[118:121], v[160:163], v[176:179], v[118:121]
	v_mfma_f32_16x16x32_bf16 v[114:117], v[168:171], v[176:179], v[114:117]
	v_mfma_f32_16x16x32_bf16 v[102:105], v[160:163], v[184:187], v[102:105]
	v_mfma_f32_16x16x32_bf16 v[98:101], v[168:171], v[184:187], v[98:101]
	v_mfma_f32_16x16x32_bf16 v[86:89], v[160:163], v[202:205], v[86:89]
	v_mfma_f32_16x16x32_bf16 v[82:85], v[168:171], v[202:205], v[82:85]
	v_mfma_f32_16x16x32_bf16 v[70:73], v[160:163], v[210:213], v[70:73]
	v_mfma_f32_16x16x32_bf16 v[66:69], v[168:171], v[210:213], v[66:69]
	v_mfma_f32_16x16x32_bf16 v[118:121], v[164:167], v[180:183], v[118:121]
	v_mfma_f32_16x16x32_bf16 v[114:117], v[172:175], v[180:183], v[114:117]
	v_mfma_f32_16x16x32_bf16 v[102:105], v[164:167], v[188:191], v[102:105]
	v_mfma_f32_16x16x32_bf16 v[98:101], v[172:175], v[188:191], v[98:101]
	v_mfma_f32_16x16x32_bf16 v[86:89], v[164:167], v[206:209], v[86:89]
	v_mfma_f32_16x16x32_bf16 v[82:85], v[172:175], v[206:209], v[82:85]
	v_mfma_f32_16x16x32_bf16 v[70:73], v[164:167], v[214:217], v[70:73]
	v_mfma_f32_16x16x32_bf16 v[66:69], v[172:175], v[214:217], v[66:69]
	s_barrier
	s_setprio 1
	s_add_i32 s51, s51, s36
	v_lshl_add_u64 v[192:193], s[22:23], 0, v[194:195]
	s_mov_b32 m0, s51
	ds_read_b128 v[176:179], v147 offset:16384
	ds_read_b128 v[180:183], v147 offset:17408
	ds_read_b128 v[184:187], v147 offset:18432
	ds_read_b128 v[188:191], v147 offset:19456
	ds_read_b128 v[202:205], v147 offset:20480
	ds_read_b128 v[206:209], v147 offset:21504
	ds_read_b128 v[210:213], v147 offset:22528
	ds_read_b128 v[214:217], v147 offset:23552
	global_load_lds_dwordx4 v[192:193], off
	s_add_i32 m0, s51, 0x2000
	s_add_u32 s52, s22, 0x40000
	v_lshl_add_u64 v[218:219], s[22:23], 0, v[134:135]
	s_addc_u32 s53, s23, 0
	s_add_i32 s51, s54, s36
	global_load_lds_dwordx4 v[218:219], off
	v_lshl_add_u64 v[220:221], s[52:53], 0, v[194:195]
	s_mov_b32 m0, s51
	v_lshl_add_u64 v[222:223], s[24:25], 0, v[132:133]
	global_load_lds_dwordx4 v[220:221], off
	v_lshl_add_u64 v[220:221], s[52:53], 0, v[134:135]
	s_add_i32 m0, s51, 0x2000
	s_nop 0
	global_load_lds_dwordx4 v[220:221], off
	v_lshl_add_u64 v[220:221], s[24:25], 0, v[130:131]
	s_mov_b32 m0, s19
	s_nop 0
	global_load_lds_dwordx4 v[220:221], off
	s_mov_b32 m0, s37
	s_nop 0
	global_load_lds_dwordx4 v[222:223], off
	s_waitcnt vmcnt(8)
	s_waitcnt lgkmcnt(0)
	s_setprio 0
	s_barrier
	s_waitcnt lgkmcnt(0)
	v_mfma_f32_16x16x32_bf16 v[62:65], v[140:143], v[176:179], v[62:65]
	v_mfma_f32_16x16x32_bf16 v[58:61], v[152:155], v[176:179], v[58:61]
	v_mfma_f32_16x16x32_bf16 v[46:49], v[140:143], v[184:187], v[46:49]
	v_mfma_f32_16x16x32_bf16 v[42:45], v[152:155], v[184:187], v[42:45]
	v_mfma_f32_16x16x32_bf16 v[30:33], v[140:143], v[202:205], v[30:33]
	v_mfma_f32_16x16x32_bf16 v[26:29], v[152:155], v[202:205], v[26:29]
	v_mfma_f32_16x16x32_bf16 v[14:17], v[140:143], v[210:213], v[14:17]
	v_mfma_f32_16x16x32_bf16 v[10:13], v[152:155], v[210:213], v[10:13]
	v_mfma_f32_16x16x32_bf16 v[62:65], v[148:151], v[180:183], v[62:65]
	v_mfma_f32_16x16x32_bf16 v[58:61], v[156:159], v[180:183], v[58:61]
	v_mfma_f32_16x16x32_bf16 v[46:49], v[148:151], v[188:191], v[46:49]
	v_mfma_f32_16x16x32_bf16 v[42:45], v[156:159], v[188:191], v[42:45]
	v_mfma_f32_16x16x32_bf16 v[30:33], v[148:151], v[206:209], v[30:33]
	v_mfma_f32_16x16x32_bf16 v[26:29], v[156:159], v[206:209], v[26:29]
	v_mfma_f32_16x16x32_bf16 v[14:17], v[148:151], v[214:217], v[14:17]
	v_mfma_f32_16x16x32_bf16 v[10:13], v[156:159], v[214:217], v[10:13]
	v_mfma_f32_16x16x32_bf16 v[54:57], v[160:163], v[176:179], v[54:57]
	v_mfma_f32_16x16x32_bf16 v[50:53], v[168:171], v[176:179], v[50:53]
	v_mfma_f32_16x16x32_bf16 v[38:41], v[160:163], v[184:187], v[38:41]
	v_mfma_f32_16x16x32_bf16 v[34:37], v[168:171], v[184:187], v[34:37]
	v_mfma_f32_16x16x32_bf16 v[22:25], v[160:163], v[202:205], v[22:25]
	v_mfma_f32_16x16x32_bf16 v[18:21], v[168:171], v[202:205], v[18:21]
	v_mfma_f32_16x16x32_bf16 v[6:9], v[160:163], v[210:213], v[6:9]
	v_mfma_f32_16x16x32_bf16 v[2:5], v[168:171], v[210:213], v[2:5]
	v_mfma_f32_16x16x32_bf16 v[54:57], v[164:167], v[180:183], v[54:57]
	v_mfma_f32_16x16x32_bf16 v[50:53], v[172:175], v[180:183], v[50:53]
	v_mfma_f32_16x16x32_bf16 v[38:41], v[164:167], v[188:191], v[38:41]
	v_mfma_f32_16x16x32_bf16 v[34:37], v[172:175], v[188:191], v[34:37]
	v_mfma_f32_16x16x32_bf16 v[22:25], v[164:167], v[206:209], v[22:25]
	v_mfma_f32_16x16x32_bf16 v[18:21], v[172:175], v[206:209], v[18:21]
	v_mfma_f32_16x16x32_bf16 v[6:9], v[164:167], v[214:217], v[6:9]
	v_mfma_f32_16x16x32_bf16 v[2:5], v[172:175], v[214:217], v[2:5]
	s_barrier
	s_setprio 1
	s_add_i32 s51, 0, 0x18000
	s_add_i32 s52, 0, 0x1c000
	v_add_u32_e32 v156, s51, v145
	v_add_u32_e32 v172, s52, v145
	ds_read_b128 v[140:143], v156
	ds_read_b128 v[148:151], v156 offset:1024
	ds_read_b128 v[152:155], v156 offset:2048
	ds_read_b128 v[156:159], v156 offset:3072
	ds_read_b128 v[160:163], v172
	ds_read_b128 v[164:167], v172 offset:1024
	ds_read_b128 v[168:171], v172 offset:2048
	ds_read_b128 v[172:175], v172 offset:3072
	s_add_u32 s24, s24, 0x40000
	s_addc_u32 s25, s25, 0
	s_mov_b32 m0, s38
	v_lshl_add_u64 v[224:225], s[24:25], 0, v[130:131]
	ds_read_b128 v[176:179], v147 offset:32768
	ds_read_b128 v[180:183], v147 offset:33792
	ds_read_b128 v[184:187], v147 offset:34816
	ds_read_b128 v[188:191], v147 offset:35840
	ds_read_b128 v[202:205], v147 offset:36864
	ds_read_b128 v[206:209], v147 offset:37888
	ds_read_b128 v[210:213], v147 offset:38912
	ds_read_b128 v[214:217], v147 offset:39936
	global_load_lds_dwordx4 v[224:225], off
	v_lshl_add_u64 v[224:225], s[24:25], 0, v[132:133]
	s_mov_b32 m0, s39
	s_nop 0
	global_load_lds_dwordx4 v[224:225], off
	s_waitcnt vmcnt(8)
	s_waitcnt lgkmcnt(0)
	s_setprio 0
	s_barrier
	s_waitcnt lgkmcnt(0)
	v_mfma_f32_16x16x32_bf16 v[126:129], v[140:143], v[176:179], v[126:129]
	v_mfma_f32_16x16x32_bf16 v[122:125], v[152:155], v[176:179], v[122:125]
	v_mfma_f32_16x16x32_bf16 v[110:113], v[140:143], v[184:187], v[110:113]
	v_mfma_f32_16x16x32_bf16 v[106:109], v[152:155], v[184:187], v[106:109]
	v_mfma_f32_16x16x32_bf16 v[94:97], v[140:143], v[202:205], v[94:97]
	v_mfma_f32_16x16x32_bf16 v[90:93], v[152:155], v[202:205], v[90:93]
	v_mfma_f32_16x16x32_bf16 v[78:81], v[140:143], v[210:213], v[78:81]
	v_mfma_f32_16x16x32_bf16 v[74:77], v[152:155], v[210:213], v[74:77]
	v_mfma_f32_16x16x32_bf16 v[126:129], v[148:151], v[180:183], v[126:129]
	v_mfma_f32_16x16x32_bf16 v[122:125], v[156:159], v[180:183], v[122:125]
	v_mfma_f32_16x16x32_bf16 v[110:113], v[148:151], v[188:191], v[110:113]
	v_mfma_f32_16x16x32_bf16 v[106:109], v[156:159], v[188:191], v[106:109]
	v_mfma_f32_16x16x32_bf16 v[94:97], v[148:151], v[206:209], v[94:97]
	v_mfma_f32_16x16x32_bf16 v[90:93], v[156:159], v[206:209], v[90:93]
	v_mfma_f32_16x16x32_bf16 v[78:81], v[148:151], v[214:217], v[78:81]
	v_mfma_f32_16x16x32_bf16 v[74:77], v[156:159], v[214:217], v[74:77]
	v_mfma_f32_16x16x32_bf16 v[118:121], v[160:163], v[176:179], v[118:121]
	v_mfma_f32_16x16x32_bf16 v[114:117], v[168:171], v[176:179], v[114:117]
	v_mfma_f32_16x16x32_bf16 v[102:105], v[160:163], v[184:187], v[102:105]
	v_mfma_f32_16x16x32_bf16 v[98:101], v[168:171], v[184:187], v[98:101]
	v_mfma_f32_16x16x32_bf16 v[86:89], v[160:163], v[202:205], v[86:89]
	v_mfma_f32_16x16x32_bf16 v[82:85], v[168:171], v[202:205], v[82:85]
	v_mfma_f32_16x16x32_bf16 v[70:73], v[160:163], v[210:213], v[70:73]
	v_mfma_f32_16x16x32_bf16 v[66:69], v[168:171], v[210:213], v[66:69]
	v_mfma_f32_16x16x32_bf16 v[118:121], v[164:167], v[180:183], v[118:121]
	v_mfma_f32_16x16x32_bf16 v[114:117], v[172:175], v[180:183], v[114:117]
	v_mfma_f32_16x16x32_bf16 v[102:105], v[164:167], v[188:191], v[102:105]
	v_mfma_f32_16x16x32_bf16 v[98:101], v[172:175], v[188:191], v[98:101]
	v_mfma_f32_16x16x32_bf16 v[86:89], v[164:167], v[206:209], v[86:89]
	v_mfma_f32_16x16x32_bf16 v[82:85], v[172:175], v[206:209], v[82:85]
	v_mfma_f32_16x16x32_bf16 v[70:73], v[164:167], v[214:217], v[70:73]
	v_mfma_f32_16x16x32_bf16 v[66:69], v[172:175], v[214:217], v[66:69]
	s_barrier
	s_setprio 1
	s_add_i32 s24, s51, s36
	v_lshl_add_u64 v[192:193], v[192:193], 0, s[92:93]
	s_mov_b32 m0, s24
	ds_read_b128 v[176:179], v147 offset:49152
	ds_read_b128 v[180:183], v147 offset:50176
	ds_read_b128 v[184:187], v147 offset:51200
	ds_read_b128 v[188:191], v147 offset:52224
	ds_read_b128 v[202:205], v147 offset:53248
	ds_read_b128 v[206:209], v147 offset:54272
	ds_read_b128 v[210:213], v147 offset:55296
	ds_read_b128 v[214:217], v147 offset:56320
	global_load_lds_dwordx4 v[192:193], off
	s_add_i32 m0, s24, 0x2000
	s_add_u32 s22, s22, 0x40080
	v_lshl_add_u64 v[192:193], v[218:219], 0, s[92:93]
	s_addc_u32 s23, s23, 0
	s_add_i32 s24, s52, s36
	global_load_lds_dwordx4 v[192:193], off
	v_lshl_add_u64 v[192:193], s[22:23], 0, v[194:195]
	s_mov_b32 m0, s24
	s_nop 0
	global_load_lds_dwordx4 v[192:193], off
	v_lshl_add_u64 v[192:193], s[22:23], 0, v[134:135]
	s_add_i32 m0, s24, 0x2000
	s_nop 0
	global_load_lds_dwordx4 v[192:193], off
	v_lshl_add_u64 v[192:193], v[220:221], 0, s[92:93]
	s_mov_b32 m0, s42
	s_nop 0
	global_load_lds_dwordx4 v[192:193], off
	v_lshl_add_u64 v[192:193], v[222:223], 0, s[92:93]
	s_mov_b32 m0, s43
	s_nop 0
	global_load_lds_dwordx4 v[192:193], off
	s_waitcnt vmcnt(8)
	s_waitcnt lgkmcnt(0)
	s_setprio 0
	s_barrier
	s_waitcnt lgkmcnt(0)
	v_mfma_f32_16x16x32_bf16 v[62:65], v[140:143], v[176:179], v[62:65]
	v_mfma_f32_16x16x32_bf16 v[58:61], v[152:155], v[176:179], v[58:61]
	v_mfma_f32_16x16x32_bf16 v[46:49], v[140:143], v[184:187], v[46:49]
	v_mfma_f32_16x16x32_bf16 v[42:45], v[152:155], v[184:187], v[42:45]
	v_mfma_f32_16x16x32_bf16 v[30:33], v[140:143], v[202:205], v[30:33]
	v_mfma_f32_16x16x32_bf16 v[26:29], v[152:155], v[202:205], v[26:29]
	v_mfma_f32_16x16x32_bf16 v[14:17], v[140:143], v[210:213], v[14:17]
	v_mfma_f32_16x16x32_bf16 v[10:13], v[152:155], v[210:213], v[10:13]
	v_mfma_f32_16x16x32_bf16 v[62:65], v[148:151], v[180:183], v[62:65]
	v_mfma_f32_16x16x32_bf16 v[58:61], v[156:159], v[180:183], v[58:61]
	v_mfma_f32_16x16x32_bf16 v[46:49], v[148:151], v[188:191], v[46:49]
	v_mfma_f32_16x16x32_bf16 v[42:45], v[156:159], v[188:191], v[42:45]
	v_mfma_f32_16x16x32_bf16 v[30:33], v[148:151], v[206:209], v[30:33]
	v_mfma_f32_16x16x32_bf16 v[26:29], v[156:159], v[206:209], v[26:29]
	v_mfma_f32_16x16x32_bf16 v[14:17], v[148:151], v[214:217], v[14:17]
	v_mfma_f32_16x16x32_bf16 v[10:13], v[156:159], v[214:217], v[10:13]
	v_mfma_f32_16x16x32_bf16 v[54:57], v[160:163], v[176:179], v[54:57]
	v_mfma_f32_16x16x32_bf16 v[50:53], v[168:171], v[176:179], v[50:53]
	v_mfma_f32_16x16x32_bf16 v[38:41], v[160:163], v[184:187], v[38:41]
	v_mfma_f32_16x16x32_bf16 v[34:37], v[168:171], v[184:187], v[34:37]
	v_mfma_f32_16x16x32_bf16 v[22:25], v[160:163], v[202:205], v[22:25]
	v_mfma_f32_16x16x32_bf16 v[18:21], v[168:171], v[202:205], v[18:21]
	v_mfma_f32_16x16x32_bf16 v[6:9], v[160:163], v[210:213], v[6:9]
	v_mfma_f32_16x16x32_bf16 v[2:5], v[168:171], v[210:213], v[2:5]
	v_mfma_f32_16x16x32_bf16 v[54:57], v[164:167], v[180:183], v[54:57]
	v_mfma_f32_16x16x32_bf16 v[50:53], v[172:175], v[180:183], v[50:53]
	v_mfma_f32_16x16x32_bf16 v[38:41], v[164:167], v[188:191], v[38:41]
	v_mfma_f32_16x16x32_bf16 v[34:37], v[172:175], v[188:191], v[34:37]
	v_mfma_f32_16x16x32_bf16 v[22:25], v[164:167], v[206:209], v[22:25]
	v_mfma_f32_16x16x32_bf16 v[18:21], v[172:175], v[206:209], v[18:21]
	v_mfma_f32_16x16x32_bf16 v[6:9], v[164:167], v[214:217], v[6:9]
	v_mfma_f32_16x16x32_bf16 v[2:5], v[172:175], v[214:217], v[2:5]
	s_barrier
	s_add_i32 s50, s50, 2
	s_add_u32 s20, s20, 0x100
	s_addc_u32 s21, s21, 0
	s_add_u32 s48, s48, 0x100
	s_addc_u32 s49, s49, 0
	s_cmp_gt_u32 s50, 13
	s_cbranch_scc0 .LBB0_1040
	s_and_b64 vcc, exec, s[8:9]
	s_cbranch_vccz .LBB0_1043
	s_barrier

.LBB0_1130:
	s_setprio 1
	s_add_u32 s28, s26, 0xfff00080
	s_addc_u32 s29, s27, -1
	s_add_i32 s56, 0, 0x10000
	s_cmp_eq_u32 s55, 60
	s_cselect_b32 s31, s7, s29
	s_cselect_b32 s30, s9, s28
	s_cselect_b32 s29, s19, s54
	s_cselect_b32 s28, s21, s53
	s_add_i32 s58, 0, 0x14000
	v_add_u32_e32 v152, s56, v167
	v_add_u32_e32 v164, s58, v167
	ds_read_b128 v[130:133], v152
	ds_read_b128 v[134:137], v152 offset:1024
	ds_read_b128 v[138:141], v152 offset:2048
	ds_read_b128 v[152:155], v152 offset:3072
	ds_read_b128 v[156:159], v164
	ds_read_b128 v[160:163], v164 offset:1024
	ds_read_b128 v[170:173], v164 offset:2048
	ds_read_b128 v[174:177], v164 offset:3072
	v_lshl_add_u64 v[164:165], s[26:27], 0, v[148:149]
	s_add_i32 m0, s44, 0xc000
	ds_read_b128 v[178:181], v169
	ds_read_b128 v[182:185], v169 offset:1024
	ds_read_b128 v[186:189], v169 offset:2048
	ds_read_b128 v[190:193], v169 offset:3072
	ds_read_b128 v[202:205], v169 offset:4096
	ds_read_b128 v[206:209], v169 offset:5120
	ds_read_b128 v[210:213], v169 offset:6144
	ds_read_b128 v[214:217], v169 offset:7168
	global_load_lds_dwordx4 v[164:165], off
	v_lshl_add_u64 v[164:165], s[26:27], 0, v[150:151]
	s_add_i32 m0, s44, 0xe000
	s_nop 0
	global_load_lds_dwordx4 v[164:165], off
	s_waitcnt vmcnt(8)
	s_waitcnt lgkmcnt(0)
	s_setprio 0
	s_barrier
	s_waitcnt lgkmcnt(0)
	v_mfma_f32_16x16x32_bf16 v[126:129], v[130:133], v[178:181], v[126:129]
	v_mfma_f32_16x16x32_bf16 v[122:125], v[138:141], v[178:181], v[122:125]
	v_mfma_f32_16x16x32_bf16 v[110:113], v[130:133], v[186:189], v[110:113]
	v_mfma_f32_16x16x32_bf16 v[106:109], v[138:141], v[186:189], v[106:109]
	v_mfma_f32_16x16x32_bf16 v[94:97], v[130:133], v[202:205], v[94:97]
	v_mfma_f32_16x16x32_bf16 v[90:93], v[138:141], v[202:205], v[90:93]
	v_mfma_f32_16x16x32_bf16 v[78:81], v[130:133], v[210:213], v[78:81]
	v_mfma_f32_16x16x32_bf16 v[74:77], v[138:141], v[210:213], v[74:77]
	v_mfma_f32_16x16x32_bf16 v[126:129], v[134:137], v[182:185], v[126:129]
	v_mfma_f32_16x16x32_bf16 v[122:125], v[152:155], v[182:185], v[122:125]
	v_mfma_f32_16x16x32_bf16 v[110:113], v[134:137], v[190:193], v[110:113]
	v_mfma_f32_16x16x32_bf16 v[106:109], v[152:155], v[190:193], v[106:109]
	v_mfma_f32_16x16x32_bf16 v[94:97], v[134:137], v[206:209], v[94:97]
	v_mfma_f32_16x16x32_bf16 v[90:93], v[152:155], v[206:209], v[90:93]
	v_mfma_f32_16x16x32_bf16 v[78:81], v[134:137], v[214:217], v[78:81]
	v_mfma_f32_16x16x32_bf16 v[74:77], v[152:155], v[214:217], v[74:77]
	v_mfma_f32_16x16x32_bf16 v[118:121], v[156:159], v[178:181], v[118:121]
	v_mfma_f32_16x16x32_bf16 v[114:117], v[170:173], v[178:181], v[114:117]
	v_mfma_f32_16x16x32_bf16 v[102:105], v[156:159], v[186:189], v[102:105]
	v_mfma_f32_16x16x32_bf16 v[98:101], v[170:173], v[186:189], v[98:101]
	v_mfma_f32_16x16x32_bf16 v[86:89], v[156:159], v[202:205], v[86:89]
	v_mfma_f32_16x16x32_bf16 v[82:85], v[170:173], v[202:205], v[82:85]
	v_mfma_f32_16x16x32_bf16 v[70:73], v[156:159], v[210:213], v[70:73]
	v_mfma_f32_16x16x32_bf16 v[66:69], v[170:173], v[210:213], v[66:69]
	v_mfma_f32_16x16x32_bf16 v[118:121], v[160:163], v[182:185], v[118:121]
	v_mfma_f32_16x16x32_bf16 v[114:117], v[174:177], v[182:185], v[114:117]
	v_mfma_f32_16x16x32_bf16 v[102:105], v[160:163], v[190:193], v[102:105]
	v_mfma_f32_16x16x32_bf16 v[98:101], v[174:177], v[190:193], v[98:101]
	v_mfma_f32_16x16x32_bf16 v[86:89], v[160:163], v[206:209], v[86:89]
	v_mfma_f32_16x16x32_bf16 v[82:85], v[174:177], v[206:209], v[82:85]
	v_mfma_f32_16x16x32_bf16 v[70:73], v[160:163], v[214:217], v[70:73]
	v_mfma_f32_16x16x32_bf16 v[66:69], v[174:177], v[214:217], v[66:69]
	s_barrier
	s_setprio 1
	s_add_i32 s56, s56, s43
	v_lshl_add_u64 v[164:165], s[28:29], 0, v[194:195]
	s_mov_b32 m0, s56
	ds_read_b128 v[178:181], v169 offset:16384
	ds_read_b128 v[182:185], v169 offset:17408
	ds_read_b128 v[186:189], v169 offset:18432
	ds_read_b128 v[190:193], v169 offset:19456
	ds_read_b128 v[202:205], v169 offset:20480
	ds_read_b128 v[206:209], v169 offset:21504
	ds_read_b128 v[210:213], v169 offset:22528
	ds_read_b128 v[214:217], v169 offset:23552
	global_load_lds_dwordx4 v[164:165], off
	s_add_i32 m0, s56, 0x2000
	s_add_u32 s56, s28, 0x100000
	v_lshl_add_u64 v[218:219], s[28:29], 0, v[146:147]
	s_addc_u32 s57, s29, 0
	s_add_i32 s58, s58, s43
	global_load_lds_dwordx4 v[218:219], off
	v_lshl_add_u64 v[220:221], s[56:57], 0, v[194:195]
	s_mov_b32 m0, s58
	v_lshl_add_u64 v[222:223], s[30:31], 0, v[144:145]
	global_load_lds_dwordx4 v[220:221], off
	v_lshl_add_u64 v[220:221], s[56:57], 0, v[146:147]
	s_add_i32 m0, s58, 0x2000
	s_nop 0
	global_load_lds_dwordx4 v[220:221], off
	v_lshl_add_u64 v[220:221], s[30:31], 0, v[142:143]
	s_mov_b32 m0, s44
	s_nop 0
	global_load_lds_dwordx4 v[220:221], off
	s_mov_b32 m0, s45
	s_nop 0
	global_load_lds_dwordx4 v[222:223], off
	s_waitcnt vmcnt(8)
	s_waitcnt lgkmcnt(0)
	s_setprio 0
	s_barrier
	s_waitcnt lgkmcnt(0)
	v_mfma_f32_16x16x32_bf16 v[62:65], v[130:133], v[178:181], v[62:65]
	v_mfma_f32_16x16x32_bf16 v[58:61], v[138:141], v[178:181], v[58:61]
	v_mfma_f32_16x16x32_bf16 v[46:49], v[130:133], v[186:189], v[46:49]
	v_mfma_f32_16x16x32_bf16 v[42:45], v[138:141], v[186:189], v[42:45]
	v_mfma_f32_16x16x32_bf16 v[30:33], v[130:133], v[202:205], v[30:33]
	v_mfma_f32_16x16x32_bf16 v[26:29], v[138:141], v[202:205], v[26:29]
	v_mfma_f32_16x16x32_bf16 v[14:17], v[130:133], v[210:213], v[14:17]
	v_mfma_f32_16x16x32_bf16 v[10:13], v[138:141], v[210:213], v[10:13]
	v_mfma_f32_16x16x32_bf16 v[62:65], v[134:137], v[182:185], v[62:65]
	v_mfma_f32_16x16x32_bf16 v[58:61], v[152:155], v[182:185], v[58:61]
	v_mfma_f32_16x16x32_bf16 v[46:49], v[134:137], v[190:193], v[46:49]
	v_mfma_f32_16x16x32_bf16 v[42:45], v[152:155], v[190:193], v[42:45]
	v_mfma_f32_16x16x32_bf16 v[30:33], v[134:137], v[206:209], v[30:33]
	v_mfma_f32_16x16x32_bf16 v[26:29], v[152:155], v[206:209], v[26:29]
	v_mfma_f32_16x16x32_bf16 v[14:17], v[134:137], v[214:217], v[14:17]
	v_mfma_f32_16x16x32_bf16 v[10:13], v[152:155], v[214:217], v[10:13]
	v_mfma_f32_16x16x32_bf16 v[54:57], v[156:159], v[178:181], v[54:57]
	v_mfma_f32_16x16x32_bf16 v[50:53], v[170:173], v[178:181], v[50:53]
	v_mfma_f32_16x16x32_bf16 v[38:41], v[156:159], v[186:189], v[38:41]
	v_mfma_f32_16x16x32_bf16 v[34:37], v[170:173], v[186:189], v[34:37]
	v_mfma_f32_16x16x32_bf16 v[22:25], v[156:159], v[202:205], v[22:25]
	v_mfma_f32_16x16x32_bf16 v[18:21], v[170:173], v[202:205], v[18:21]
	v_mfma_f32_16x16x32_bf16 v[6:9], v[156:159], v[210:213], v[6:9]
	v_mfma_f32_16x16x32_bf16 v[2:5], v[170:173], v[210:213], v[2:5]
	v_mfma_f32_16x16x32_bf16 v[54:57], v[160:163], v[182:185], v[54:57]
	v_mfma_f32_16x16x32_bf16 v[50:53], v[174:177], v[182:185], v[50:53]
	v_mfma_f32_16x16x32_bf16 v[38:41], v[160:163], v[190:193], v[38:41]
	v_mfma_f32_16x16x32_bf16 v[34:37], v[174:177], v[190:193], v[34:37]
	v_mfma_f32_16x16x32_bf16 v[22:25], v[160:163], v[206:209], v[22:25]
	v_mfma_f32_16x16x32_bf16 v[18:21], v[174:177], v[206:209], v[18:21]
	v_mfma_f32_16x16x32_bf16 v[6:9], v[160:163], v[214:217], v[6:9]
	v_mfma_f32_16x16x32_bf16 v[2:5], v[174:177], v[214:217], v[2:5]
	s_barrier
	s_setprio 1
	s_add_i32 s56, 0, 0x18000
	s_add_i32 s57, 0, 0x1c000
	v_add_u32_e32 v152, s56, v167
	v_add_u32_e32 v174, s57, v167
	ds_read_b128 v[130:133], v152
	ds_read_b128 v[134:137], v152 offset:1024
	ds_read_b128 v[138:141], v152 offset:2048
	ds_read_b128 v[152:155], v152 offset:3072
	ds_read_b128 v[156:159], v174
	ds_read_b128 v[160:163], v174 offset:1024
	ds_read_b128 v[170:173], v174 offset:2048
	ds_read_b128 v[174:177], v174 offset:3072
	s_add_u32 s30, s30, 0x100000
	s_addc_u32 s31, s31, 0
	s_mov_b32 m0, s46
	v_lshl_add_u64 v[224:225], s[30:31], 0, v[142:143]
	ds_read_b128 v[178:181], v169 offset:32768
	ds_read_b128 v[182:185], v169 offset:33792
	ds_read_b128 v[186:189], v169 offset:34816
	ds_read_b128 v[190:193], v169 offset:35840
	ds_read_b128 v[202:205], v169 offset:36864
	ds_read_b128 v[206:209], v169 offset:37888
	ds_read_b128 v[210:213], v169 offset:38912
	ds_read_b128 v[214:217], v169 offset:39936
	global_load_lds_dwordx4 v[224:225], off
	v_lshl_add_u64 v[224:225], s[30:31], 0, v[144:145]
	s_mov_b32 m0, s47
	s_nop 0
	global_load_lds_dwordx4 v[224:225], off
	s_waitcnt vmcnt(8)
	s_waitcnt lgkmcnt(0)
	s_setprio 0
	s_barrier
	s_waitcnt lgkmcnt(0)
	v_mfma_f32_16x16x32_bf16 v[126:129], v[130:133], v[178:181], v[126:129]
	v_mfma_f32_16x16x32_bf16 v[122:125], v[138:141], v[178:181], v[122:125]
	v_mfma_f32_16x16x32_bf16 v[110:113], v[130:133], v[186:189], v[110:113]
	v_mfma_f32_16x16x32_bf16 v[106:109], v[138:141], v[186:189], v[106:109]
	v_mfma_f32_16x16x32_bf16 v[94:97], v[130:133], v[202:205], v[94:97]
	v_mfma_f32_16x16x32_bf16 v[90:93], v[138:141], v[202:205], v[90:93]
	v_mfma_f32_16x16x32_bf16 v[78:81], v[130:133], v[210:213], v[78:81]
	v_mfma_f32_16x16x32_bf16 v[74:77], v[138:141], v[210:213], v[74:77]
	v_mfma_f32_16x16x32_bf16 v[126:129], v[134:137], v[182:185], v[126:129]
	v_mfma_f32_16x16x32_bf16 v[122:125], v[152:155], v[182:185], v[122:125]
	v_mfma_f32_16x16x32_bf16 v[110:113], v[134:137], v[190:193], v[110:113]
	v_mfma_f32_16x16x32_bf16 v[106:109], v[152:155], v[190:193], v[106:109]
	v_mfma_f32_16x16x32_bf16 v[94:97], v[134:137], v[206:209], v[94:97]
	v_mfma_f32_16x16x32_bf16 v[90:93], v[152:155], v[206:209], v[90:93]
	v_mfma_f32_16x16x32_bf16 v[78:81], v[134:137], v[214:217], v[78:81]
	v_mfma_f32_16x16x32_bf16 v[74:77], v[152:155], v[214:217], v[74:77]
	v_mfma_f32_16x16x32_bf16 v[118:121], v[156:159], v[178:181], v[118:121]
	v_mfma_f32_16x16x32_bf16 v[114:117], v[170:173], v[178:181], v[114:117]
	v_mfma_f32_16x16x32_bf16 v[102:105], v[156:159], v[186:189], v[102:105]
	v_mfma_f32_16x16x32_bf16 v[98:101], v[170:173], v[186:189], v[98:101]
	v_mfma_f32_16x16x32_bf16 v[86:89], v[156:159], v[202:205], v[86:89]
	v_mfma_f32_16x16x32_bf16 v[82:85], v[170:173], v[202:205], v[82:85]
	v_mfma_f32_16x16x32_bf16 v[70:73], v[156:159], v[210:213], v[70:73]
	v_mfma_f32_16x16x32_bf16 v[66:69], v[170:173], v[210:213], v[66:69]
	v_mfma_f32_16x16x32_bf16 v[118:121], v[160:163], v[182:185], v[118:121]
	v_mfma_f32_16x16x32_bf16 v[114:117], v[174:177], v[182:185], v[114:117]
	v_mfma_f32_16x16x32_bf16 v[102:105], v[160:163], v[190:193], v[102:105]
	v_mfma_f32_16x16x32_bf16 v[98:101], v[174:177], v[190:193], v[98:101]
	v_mfma_f32_16x16x32_bf16 v[86:89], v[160:163], v[206:209], v[86:89]
	v_mfma_f32_16x16x32_bf16 v[82:85], v[174:177], v[206:209], v[82:85]
	v_mfma_f32_16x16x32_bf16 v[70:73], v[160:163], v[214:217], v[70:73]
	v_mfma_f32_16x16x32_bf16 v[66:69], v[174:177], v[214:217], v[66:69]
	s_barrier
	s_setprio 1
	s_add_i32 s30, s56, s43
	v_lshl_add_u64 v[164:165], v[164:165], 0, s[92:93]
	s_mov_b32 m0, s30
	ds_read_b128 v[178:181], v169 offset:49152
	ds_read_b128 v[182:185], v169 offset:50176
	ds_read_b128 v[186:189], v169 offset:51200
	ds_read_b128 v[190:193], v169 offset:52224
	ds_read_b128 v[202:205], v169 offset:53248
	ds_read_b128 v[206:209], v169 offset:54272
	ds_read_b128 v[210:213], v169 offset:55296
	ds_read_b128 v[214:217], v169 offset:56320
	global_load_lds_dwordx4 v[164:165], off
	s_add_i32 m0, s30, 0x2000
	s_add_u32 s28, s28, 0x100080
	v_lshl_add_u64 v[164:165], v[218:219], 0, s[92:93]
	s_addc_u32 s29, s29, 0
	s_add_i32 s30, s57, s43
	global_load_lds_dwordx4 v[164:165], off
	v_lshl_add_u64 v[164:165], s[28:29], 0, v[194:195]
	s_mov_b32 m0, s30
	s_nop 0
	global_load_lds_dwordx4 v[164:165], off
	v_lshl_add_u64 v[164:165], s[28:29], 0, v[146:147]
	s_add_i32 m0, s30, 0x2000
	s_nop 0
	global_load_lds_dwordx4 v[164:165], off
	v_lshl_add_u64 v[164:165], v[220:221], 0, s[92:93]
	s_mov_b32 m0, s49
	s_nop 0
	global_load_lds_dwordx4 v[164:165], off
	v_lshl_add_u64 v[164:165], v[222:223], 0, s[92:93]
	s_mov_b32 m0, s50
	s_nop 0
	global_load_lds_dwordx4 v[164:165], off
	s_waitcnt vmcnt(8)
	s_waitcnt lgkmcnt(0)
	s_setprio 0
	s_barrier
	s_waitcnt lgkmcnt(0)
	v_mfma_f32_16x16x32_bf16 v[62:65], v[130:133], v[178:181], v[62:65]
	v_mfma_f32_16x16x32_bf16 v[58:61], v[138:141], v[178:181], v[58:61]
	v_mfma_f32_16x16x32_bf16 v[46:49], v[130:133], v[186:189], v[46:49]
	v_mfma_f32_16x16x32_bf16 v[42:45], v[138:141], v[186:189], v[42:45]
	v_mfma_f32_16x16x32_bf16 v[30:33], v[130:133], v[202:205], v[30:33]
	v_mfma_f32_16x16x32_bf16 v[26:29], v[138:141], v[202:205], v[26:29]
	v_mfma_f32_16x16x32_bf16 v[14:17], v[130:133], v[210:213], v[14:17]
	v_mfma_f32_16x16x32_bf16 v[10:13], v[138:141], v[210:213], v[10:13]
	v_mfma_f32_16x16x32_bf16 v[62:65], v[134:137], v[182:185], v[62:65]
	v_mfma_f32_16x16x32_bf16 v[58:61], v[152:155], v[182:185], v[58:61]
	v_mfma_f32_16x16x32_bf16 v[46:49], v[134:137], v[190:193], v[46:49]
	v_mfma_f32_16x16x32_bf16 v[42:45], v[152:155], v[190:193], v[42:45]
	v_mfma_f32_16x16x32_bf16 v[30:33], v[134:137], v[206:209], v[30:33]
	v_mfma_f32_16x16x32_bf16 v[26:29], v[152:155], v[206:209], v[26:29]
	v_mfma_f32_16x16x32_bf16 v[14:17], v[134:137], v[214:217], v[14:17]
	v_mfma_f32_16x16x32_bf16 v[10:13], v[152:155], v[214:217], v[10:13]
	v_mfma_f32_16x16x32_bf16 v[54:57], v[156:159], v[178:181], v[54:57]
	v_mfma_f32_16x16x32_bf16 v[50:53], v[170:173], v[178:181], v[50:53]
	v_mfma_f32_16x16x32_bf16 v[38:41], v[156:159], v[186:189], v[38:41]
	v_mfma_f32_16x16x32_bf16 v[34:37], v[170:173], v[186:189], v[34:37]
	v_mfma_f32_16x16x32_bf16 v[22:25], v[156:159], v[202:205], v[22:25]
	v_mfma_f32_16x16x32_bf16 v[18:21], v[170:173], v[202:205], v[18:21]
	v_mfma_f32_16x16x32_bf16 v[6:9], v[156:159], v[210:213], v[6:9]
	v_mfma_f32_16x16x32_bf16 v[2:5], v[170:173], v[210:213], v[2:5]
	v_mfma_f32_16x16x32_bf16 v[54:57], v[160:163], v[182:185], v[54:57]
	v_mfma_f32_16x16x32_bf16 v[50:53], v[174:177], v[182:185], v[50:53]
	v_mfma_f32_16x16x32_bf16 v[38:41], v[160:163], v[190:193], v[38:41]
	v_mfma_f32_16x16x32_bf16 v[34:37], v[174:177], v[190:193], v[34:37]
	v_mfma_f32_16x16x32_bf16 v[22:25], v[160:163], v[206:209], v[22:25]
	v_mfma_f32_16x16x32_bf16 v[18:21], v[174:177], v[206:209], v[18:21]
	v_mfma_f32_16x16x32_bf16 v[6:9], v[160:163], v[214:217], v[6:9]
	v_mfma_f32_16x16x32_bf16 v[2:5], v[174:177], v[214:217], v[2:5]
	s_barrier
	s_add_i32 s55, s55, 2
	s_add_u32 s26, s26, 0x100
	s_addc_u32 s27, s27, 0
	s_add_u32 s53, s53, 0x100
	s_addc_u32 s54, s54, 0
	s_cmp_gt_u32 s55, 61
	s_cbranch_scc0 .LBB0_1130
	v_lshl_add_u32 v154, s6, 8, v166
	v_lshl_or_b32 v152, s8, 8, v168
	v_ashrrev_i32_e32 v155, 31, v154
	v_lshlrev_b64 v[130:131], 11, v[154:155]
	v_ashrrev_i32_e32 v153, 31, v152
	v_or_b32_e32 v156, 16, v154
	v_lshl_add_u64 v[130:131], s[12:13], 0, v[130:131]
	v_lshlrev_b64 v[132:133], 1, v[152:153]
	v_ashrrev_i32_e32 v157, 31, v156
	v_lshl_add_u64 v[160:161], v[130:131], 0, v[132:133]
	v_lshlrev_b64 v[130:131], 11, v[156:157]
	global_load_dwordx4 v[170:173], v[160:161], off
	global_load_dwordx4 v[138:141], v[160:161], off offset:256
	v_lshl_add_u64 v[130:131], s[12:13], 0, v[130:131]
	v_lshl_add_u64 v[158:159], v[130:131], 0, v[132:133]
	global_load_dwordx4 v[134:137], v[158:159], off
	global_load_dwordx4 v[130:133], v[158:159], off offset:256
	v_cndmask_b32_e64 v162, 0, 1, s[16:17]
	v_cmp_ne_u32_e64 s[6:7], 1, v162
	v_lshlrev_b64 v[162:163], 10, v[154:155]
	v_lshl_add_u64 v[162:163], v[162:163], 0, v[152:153]
	s_andn2_b64 vcc, exec, s[16:17]
	s_waitcnt vmcnt(0)
	v_lshlrev_b32_e32 v164, 16, v170
	v_and_b32_e32 v165, 0xffff0000, v170
	v_lshlrev_b32_e32 v170, 16, v171
	v_and_b32_e32 v171, 0xffff0000, v171
	v_lshlrev_b32_e32 v174, 16, v172
	v_and_b32_e32 v175, 0xffff0000, v172
	v_lshlrev_b32_e32 v172, 16, v173
	v_and_b32_e32 v173, 0xffff0000, v173
	v_pk_add_f32 v[126:127], v[126:127], v[164:165]
	v_pk_add_f32 v[128:129], v[128:129], v[170:171]
	v_pk_add_f32 v[122:123], v[122:123], v[174:175]
	v_pk_add_f32 v[124:125], v[124:125], v[172:173]
	v_lshl_add_u64 v[164:165], v[162:163], 2, s[14:15]
	s_cbranch_vccnz .LBB0_1210
	global_store_dwordx4 v[164:165], v[126:129], off
	global_store_dwordx4 v[164:165], v[122:125], off offset:16
	s_cbranch_execnz .LBB0_1134
